# gMLP gelu(u) loads and MIX stores lane-permuted with ds_bpermute so a lane quad touches two rows instead of four
# baseline (speedup 1.0000x reference)
; #define LAS __attribute__((address_space(3)))
; __device__ __forceinline__ unsigned pk2(float lo, float hi) { f32x2 v = {lo, hi}; bf16x2_t b = __builtin_convertvector(v, bf16x2_t); return __builtin_bit_cast(unsigned, b); }
; __device__ __forceinline__ void gmlp_unit(const GmlpP& P, int b, int ch, LAS unsigned char* lds, int wave, int lane_in) {
;     ...
;     __syncthreads();
; #pragma unroll
;     for (int nt = 0; nt < 2; ++nt) {
;         const int t = 32 * (nt == 0 ? tt0 : tt1) + r32;
;         const float tot = (ssqg[t] + ssqg[128 + t]) + (ssqg[256 + t] + ssqg[384 + t]);
;         const float r = __builtin_amdgcn_rsqf(tot * (1.0f / GW) + EPS);
;         bf16_t* op = P.MIX + (tok0 + t) * DM + AW + gI * 128 + 4 * h;
; #pragma unroll
;         for (int mt = 0; mt < 4; ++mt)
; #pragma unroll
;             for (int e4 = 0; e4 < 4; ++e4) {
;                 const f32x4 gg = *(const LAS f32x4*)(lds + LDS_GG + (gI * 128 + 32 * mt + 8 * e4 + 4 * h) * 4);
;                 u32x2 w; w.x = pk2(acc[mt][nt][4 * e4] * r * gg[0], acc[mt][nt][4 * e4 + 1] * r * gg[1]); w.y = pk2(acc[mt][nt][4 * e4 + 2] * r * gg[2], acc[mt][nt][4 * e4 + 3] * r * gg[3]);
;                 *(u32x2*)(op + 32 * mt + 8 * e4) = w;
;             }
.LBB0_536:
	s_or_b64 exec, exec, s[26:27]
	s_add_i32 s18, 0, 0x22000
	v_lshl_add_u32 v4, v157, 2, s18
	s_waitcnt lgkmcnt(0)
	s_barrier
	ds_read2st64_b32 v[2:3], v4 offset1:2
	ds_read2st64_b32 v[4:5], v4 offset0:4 offset1:6
	v_add_u32_e32 v6, s28, v144
	s_add_i32 s26, 0, 0x22800
	v_lshl_add_u32 v153, v6, 2, s26
	s_waitcnt lgkmcnt(1)
	v_mov_b32_e32 v6, v2
	s_waitcnt lgkmcnt(0)
	v_mov_b32_e32 v7, v4
	v_mov_b32_e32 v4, v3
	v_pk_add_f32 v[2:3], v[6:7], v[4:5]
	v_lshlrev_b32_e32 v140, 11, v156
	v_add_f32_e32 v2, v2, v3
	v_fmamk_f32 v2, v2, 0x3b000000, v1
	v_add_u32_e32 v4, s6, v144
	v_rsq_f32_e32 v152, v2
	v_lshl_add_u64 v[2:3], s[16:17], 0, v[140:141]
	v_lshl_add_u32 v140, v4, 2, s26
	ds_read_b128 v[6:9], v140
	v_lshlrev_b64 v[150:151], 1, v[144:145]
	v_lshl_add_u64 v[154:155], v[2:3], 0, v[150:151]
	ds_read_b128 v[2:5], v140 offset:32
	v_pk_mul_f32 v[10:11], v[114:115], v[152:153] op_sel_hi:[1,0]
	v_pk_mul_f32 v[12:13], v[116:117], v[152:153] op_sel_hi:[1,0]
	s_waitcnt lgkmcnt(1)
	v_pk_mul_f32 v[10:11], v[6:7], v[10:11]
	v_pk_mul_f32 v[12:13], v[8:9], v[12:13]
	v_cvt_pk_bf16_f32 v10, v10, v11
	v_cvt_pk_bf16_f32 v11, v12, v13
	v_and_b32_e32 v222, 32, v0
	v_lshrrev_b32_e32 v222, 2, v222
	v_mov_b32_e32 v223, 0
	v_and_b32_e32 v237, 63, v0
	v_lshrrev_b32_e32 v240, 1, v237
	v_and_b32_e32 v241, 1, v237
	v_lshl_add_u32 v236, v241, 5, v240
	v_lshlrev_b32_e32 v236, 2, v236
	v_and_b32_e32 v238, 31, v237
	v_sub_u32_e32 v238, v240, v238
	v_lshrrev_b32_e32 v239, 5, v237
	v_sub_u32_e32 v239, v241, v239
	v_lshlrev_b32_e32 v238, 11, v238
	v_lshl_add_u32 v238, v239, 4, v238
	v_ashrrev_i32_e32 v239, 31, v238
	v_lshl_add_u64 v[218:219], v[154:155], 0, v[222:223]
	v_lshl_add_u64 v[218:219], v[218:219], 0, v[238:239]
	v_mov_b32_e32 v202, v10
	v_mov_b32_e32 v203, v11
	v_pk_mul_f32 v[10:11], v[118:119], v[152:153] op_sel_hi:[1,0]
	v_pk_mul_f32 v[118:119], v[122:123], v[152:153] op_sel_hi:[1,0]
	s_waitcnt lgkmcnt(0)
	v_pk_mul_f32 v[10:11], v[2:3], v[10:11]
	v_pk_mul_f32 v[120:121], v[120:121], v[152:153] op_sel_hi:[1,0]
	v_cvt_pk_bf16_f32 v114, v10, v11
	v_pk_mul_f32 v[10:11], v[130:131], v[152:153] op_sel_hi:[1,0]
	v_pk_mul_f32 v[98:99], v[98:99], v[152:153] op_sel_hi:[1,0]
	v_pk_mul_f32 v[116:117], v[4:5], v[10:11]
	ds_read_b128 v[10:13], v140 offset:64
	v_cvt_pk_bf16_f32 v115, v116, v117
	v_mov_b32_e32 v204, v114
	v_mov_b32_e32 v205, v115
	s_nop 1
	v_permlane32_swap_b32_e32 v202, v204
	v_permlane32_swap_b32_e32 v203, v205
	ds_bpermute_b32 v202, v236, v202
	ds_bpermute_b32 v203, v236, v203
	ds_bpermute_b32 v204, v236, v204
	ds_bpermute_b32 v205, v236, v205
	ds_read_b128 v[114:117], v140 offset:96
	v_pk_mul_f32 v[100:101], v[100:101], v[152:153] op_sel_hi:[1,0]
	s_waitcnt lgkmcnt(1)
	v_pk_mul_f32 v[118:119], v[10:11], v[118:119]
	v_pk_mul_f32 v[120:121], v[12:13], v[120:121]
	v_cvt_pk_bf16_f32 v118, v118, v119
	v_cvt_pk_bf16_f32 v119, v120, v121
	v_mov_b32_e32 v206, v118
	v_mov_b32_e32 v207, v119
	v_pk_mul_f32 v[118:119], v[124:125], v[152:153] op_sel_hi:[1,0]
	v_pk_mul_f32 v[104:105], v[104:105], v[152:153] op_sel_hi:[1,0]
	s_waitcnt lgkmcnt(0)
	v_pk_mul_f32 v[118:119], v[118:119], v[114:115]
	v_pk_mul_f32 v[82:83], v[82:83], v[152:153] op_sel_hi:[1,0]
	v_cvt_pk_bf16_f32 v122, v118, v119
	v_pk_mul_f32 v[118:119], v[126:127], v[152:153] op_sel_hi:[1,0]
	v_pk_mul_f32 v[84:85], v[84:85], v[152:153] op_sel_hi:[1,0]
	v_pk_mul_f32 v[124:125], v[118:119], v[116:117]
	v_add_u32_e32 v118, s29, v144
	v_lshl_add_u32 v130, v118, 2, s26
	ds_read_b128 v[118:121], v130
	v_cvt_pk_bf16_f32 v123, v124, v125
	v_mov_b32_e32 v208, v122
	v_mov_b32_e32 v209, v123
	s_nop 1
	v_permlane32_swap_b32_e32 v206, v208
	v_permlane32_swap_b32_e32 v207, v209
	ds_bpermute_b32 v206, v236, v206
	ds_bpermute_b32 v207, v236, v207
	ds_bpermute_b32 v208, v236, v208
	ds_bpermute_b32 v209, v236, v209
	s_waitcnt lgkmcnt(4)
	global_store_dwordx4 v[218:219], v[202:205], off offset:1024
	ds_read_b128 v[122:125], v130 offset:32
	v_pk_mul_f32 v[88:89], v[88:89], v[152:153] op_sel_hi:[1,0]
	s_waitcnt lgkmcnt(1)
	v_pk_mul_f32 v[98:99], v[98:99], v[118:119]
	v_pk_mul_f32 v[100:101], v[100:101], v[120:121]
	v_cvt_pk_bf16_f32 v98, v98, v99
	v_cvt_pk_bf16_f32 v99, v100, v101
	v_mov_b32_e32 v210, v98
	v_mov_b32_e32 v211, v99
	v_pk_mul_f32 v[98:99], v[102:103], v[152:153] op_sel_hi:[1,0]
	v_pk_mul_f32 v[66:67], v[66:67], v[152:153] op_sel_hi:[1,0]
	s_waitcnt lgkmcnt(0)
	v_pk_mul_f32 v[98:99], v[98:99], v[122:123]
	v_pk_mul_f32 v[68:69], v[68:69], v[152:153] op_sel_hi:[1,0]
	v_cvt_pk_bf16_f32 v102, v98, v99
	v_pk_mul_f32 v[98:99], v[128:129], v[152:153] op_sel_hi:[1,0]
	v_pk_mul_f32 v[72:73], v[72:73], v[152:153] op_sel_hi:[1,0]
	v_pk_mul_f32 v[126:127], v[98:99], v[124:125]
	ds_read_b128 v[98:101], v130 offset:64
	v_cvt_pk_bf16_f32 v103, v126, v127
	ds_read_b128 v[126:129], v130 offset:96
	v_mov_b32_e32 v212, v102
	v_mov_b32_e32 v213, v103
	s_nop 1
	v_permlane32_swap_b32_e32 v210, v212
	v_permlane32_swap_b32_e32 v211, v213
	ds_bpermute_b32 v210, v236, v210
	ds_bpermute_b32 v211, v236, v211
	ds_bpermute_b32 v212, v236, v212
	ds_bpermute_b32 v213, v236, v213
	s_waitcnt lgkmcnt(4)
	global_store_dwordx4 v[218:219], v[206:209], off offset:1056
	v_pk_mul_f32 v[102:103], v[106:107], v[152:153] op_sel_hi:[1,0]
	s_waitcnt lgkmcnt(1)
	v_pk_mul_f32 v[104:105], v[104:105], v[100:101]
	v_pk_mul_f32 v[102:103], v[102:103], v[98:99]
	v_lshlrev_b32_e32 v140, 11, v139
	v_cvt_pk_bf16_f32 v102, v102, v103
	v_cvt_pk_bf16_f32 v103, v104, v105
	v_mov_b32_e32 v214, v102
	v_mov_b32_e32 v215, v103
	v_pk_mul_f32 v[102:103], v[108:109], v[152:153] op_sel_hi:[1,0]
	s_add_i32 s49, s49, s100
	s_waitcnt lgkmcnt(0)
; #define LAS __attribute__((address_space(3)))
; __device__ __forceinline__ unsigned pk2(float lo, float hi) { f32x2 v = {lo, hi}; bf16x2_t b = __builtin_convertvector(v, bf16x2_t); return __builtin_bit_cast(unsigned, b); }
; __device__ __forceinline__ void gmlp_unit(const GmlpP& P, int b, int ch, LAS unsigned char* lds, int wave, int lane_in) {
;     ...
; #pragma unroll
;     for (int nt = 0; nt < 2; ++nt) {
;         const int t = 32 * (nt == 0 ? tt0 : tt1) + r32;
;         const float tot = (ssqg[t] + ssqg[128 + t]) + (ssqg[256 + t] + ssqg[384 + t]);
;         const float r = __builtin_amdgcn_rsqf(tot * (1.0f / GW) + EPS);
;         bf16_t* op = P.MIX + (tok0 + t) * DM + AW + gI * 128 + 4 * h;
; #pragma unroll
;         for (int mt = 0; mt < 4; ++mt)
; #pragma unroll
;             for (int e4 = 0; e4 < 4; ++e4) {
;                 const f32x4 gg = *(const LAS f32x4*)(lds + LDS_GG + (gI * 128 + 32 * mt + 8 * e4 + 4 * h) * 4);
;                 u32x2 w; w.x = pk2(acc[mt][nt][4 * e4] * r * gg[0], acc[mt][nt][4 * e4 + 1] * r * gg[1]); w.y = pk2(acc[mt][nt][4 * e4 + 2] * r * gg[2], acc[mt][nt][4 * e4 + 3] * r * gg[3]);
;                 *(u32x2*)(op + 32 * mt + 8 * e4) = w;
;             }
	v_pk_mul_f32 v[102:103], v[102:103], v[126:127]
	s_add_i32 s38, s38, s39
	v_cvt_pk_bf16_f32 v106, v102, v103
	v_pk_mul_f32 v[102:103], v[110:111], v[152:153] op_sel_hi:[1,0]
	s_cmp_gt_i32 s49, s101
	v_pk_mul_f32 v[108:109], v[102:103], v[128:129]
	v_add_u32_e32 v102, s30, v144
	v_lshl_add_u32 v130, v102, 2, s26
	ds_read_b128 v[102:105], v130
	v_cvt_pk_bf16_f32 v107, v108, v109
	v_mov_b32_e32 v216, v106
	v_mov_b32_e32 v217, v107
	s_nop 1
	v_permlane32_swap_b32_e32 v214, v216
	v_permlane32_swap_b32_e32 v215, v217
	ds_bpermute_b32 v214, v236, v214
	ds_bpermute_b32 v215, v236, v215
	ds_bpermute_b32 v216, v236, v216
	ds_bpermute_b32 v217, v236, v217
	s_waitcnt lgkmcnt(4)
	global_store_dwordx4 v[218:219], v[210:213], off offset:1088
	ds_read_b128 v[106:109], v130 offset:32
	s_waitcnt lgkmcnt(1)
	v_pk_mul_f32 v[82:83], v[82:83], v[102:103]
	v_pk_mul_f32 v[84:85], v[84:85], v[104:105]
	v_cvt_pk_bf16_f32 v82, v82, v83
	v_cvt_pk_bf16_f32 v83, v84, v85
	v_mov_b32_e32 v202, v82
	v_mov_b32_e32 v203, v83
	v_pk_mul_f32 v[82:83], v[86:87], v[152:153] op_sel_hi:[1,0]
	s_waitcnt lgkmcnt(0)
	v_pk_mul_f32 v[82:83], v[82:83], v[106:107]
	s_nop 0
	v_cvt_pk_bf16_f32 v86, v82, v83
	v_pk_mul_f32 v[82:83], v[112:113], v[152:153] op_sel_hi:[1,0]
	s_nop 0
	v_pk_mul_f32 v[110:111], v[82:83], v[108:109]
	ds_read_b128 v[82:85], v130 offset:64
	v_cvt_pk_bf16_f32 v87, v110, v111
	ds_read_b128 v[110:113], v130 offset:96
	v_mov_b32_e32 v204, v86
	v_mov_b32_e32 v205, v87
	s_nop 1
	v_permlane32_swap_b32_e32 v202, v204
	v_permlane32_swap_b32_e32 v203, v205
	ds_bpermute_b32 v202, v236, v202
	ds_bpermute_b32 v203, v236, v203
	ds_bpermute_b32 v204, v236, v204
	ds_bpermute_b32 v205, v236, v205
	s_waitcnt lgkmcnt(4)
	global_store_dwordx4 v[218:219], v[214:217], off offset:1120
	v_pk_mul_f32 v[86:87], v[90:91], v[152:153] op_sel_hi:[1,0]
	s_waitcnt lgkmcnt(1)
	v_pk_mul_f32 v[88:89], v[88:89], v[84:85]
	v_pk_mul_f32 v[86:87], v[86:87], v[82:83]
	s_nop 0
	v_cvt_pk_bf16_f32 v86, v86, v87
	v_cvt_pk_bf16_f32 v87, v88, v89
	v_mov_b32_e32 v206, v86
	v_mov_b32_e32 v207, v87
	v_pk_mul_f32 v[86:87], v[92:93], v[152:153] op_sel_hi:[1,0]
	s_waitcnt lgkmcnt(0)
	v_pk_mul_f32 v[86:87], v[86:87], v[110:111]
	s_nop 0
	v_cvt_pk_bf16_f32 v90, v86, v87
	v_pk_mul_f32 v[86:87], v[94:95], v[152:153] op_sel_hi:[1,0]
	s_nop 0
	v_pk_mul_f32 v[92:93], v[86:87], v[112:113]
	ds_read_b128 v[86:89], v153
	v_cvt_pk_bf16_f32 v91, v92, v93
	v_mov_b32_e32 v208, v90
	v_mov_b32_e32 v209, v91
	s_nop 1
	v_permlane32_swap_b32_e32 v206, v208
	v_permlane32_swap_b32_e32 v207, v209
	ds_bpermute_b32 v206, v236, v206
	ds_bpermute_b32 v207, v236, v207
	ds_bpermute_b32 v208, v236, v208
	ds_bpermute_b32 v209, v236, v209
	s_waitcnt lgkmcnt(4)
	global_store_dwordx4 v[218:219], v[202:205], off offset:1152
	ds_read_b128 v[90:93], v153 offset:32
	s_waitcnt lgkmcnt(1)
	v_pk_mul_f32 v[66:67], v[66:67], v[86:87]
	v_pk_mul_f32 v[68:69], v[68:69], v[88:89]
	v_cvt_pk_bf16_f32 v66, v66, v67
	v_cvt_pk_bf16_f32 v67, v68, v69
	v_mov_b32_e32 v210, v66
	v_mov_b32_e32 v211, v67
	v_pk_mul_f32 v[66:67], v[70:71], v[152:153] op_sel_hi:[1,0]
	s_waitcnt lgkmcnt(0)
	v_pk_mul_f32 v[66:67], v[66:67], v[90:91]
	s_nop 0
	v_cvt_pk_bf16_f32 v70, v66, v67
	v_pk_mul_f32 v[66:67], v[96:97], v[152:153] op_sel_hi:[1,0]
	s_nop 0
	v_pk_mul_f32 v[94:95], v[66:67], v[92:93]
	ds_read_b128 v[66:69], v153 offset:64
	v_cvt_pk_bf16_f32 v71, v94, v95
	ds_read_b128 v[94:97], v153 offset:96
	v_mov_b32_e32 v212, v70
	v_mov_b32_e32 v213, v71
	s_nop 1
	v_permlane32_swap_b32_e32 v210, v212
	v_permlane32_swap_b32_e32 v211, v213
	ds_bpermute_b32 v210, v236, v210
	ds_bpermute_b32 v211, v236, v211
	ds_bpermute_b32 v212, v236, v212
	ds_bpermute_b32 v213, v236, v213
	s_waitcnt lgkmcnt(4)
	global_store_dwordx4 v[218:219], v[206:209], off offset:1184
	v_pk_mul_f32 v[70:71], v[74:75], v[152:153] op_sel_hi:[1,0]
	s_waitcnt lgkmcnt(1)
	v_pk_mul_f32 v[72:73], v[72:73], v[68:69]
	v_pk_mul_f32 v[70:71], v[70:71], v[66:67]
	s_nop 0
	v_cvt_pk_bf16_f32 v70, v70, v71
	v_cvt_pk_bf16_f32 v71, v72, v73
	v_mov_b32_e32 v214, v70
	v_mov_b32_e32 v215, v71
	v_pk_mul_f32 v[70:71], v[76:77], v[152:153] op_sel_hi:[1,0]
	v_pk_mul_f32 v[72:73], v[78:79], v[152:153] op_sel_hi:[1,0]
	s_waitcnt lgkmcnt(0)
	v_pk_mul_f32 v[70:71], v[70:71], v[94:95]
	v_pk_mul_f32 v[72:73], v[72:73], v[96:97]
	v_cvt_pk_bf16_f32 v70, v70, v71
	v_lshl_add_u32 v71, v158, 2, s18
	ds_read2st64_b32 v[74:75], v71 offset1:2
	ds_read2st64_b32 v[76:77], v71 offset0:4 offset1:6
	v_cvt_pk_bf16_f32 v71, v72, v73
	v_mov_b32_e32 v216, v70
	v_mov_b32_e32 v217, v71
	s_nop 1
	v_permlane32_swap_b32_e32 v214, v216
	v_permlane32_swap_b32_e32 v215, v217
	ds_bpermute_b32 v214, v236, v214
	ds_bpermute_b32 v215, v236, v215
	ds_bpermute_b32 v216, v236, v216
	ds_bpermute_b32 v217, v236, v217
	s_waitcnt lgkmcnt(4)
	global_store_dwordx4 v[218:219], v[210:213], off offset:1216
	v_lshl_add_u64 v[72:73], s[16:17], 0, v[140:141]
	s_waitcnt lgkmcnt(1)
	v_mov_b32_e32 v70, v74
	s_waitcnt lgkmcnt(0)
	v_mov_b32_e32 v71, v76
	v_mov_b32_e32 v76, v75
	v_pk_add_f32 v[70:71], v[70:71], v[76:77]
	v_lshl_add_u64 v[72:73], v[72:73], 0, v[150:151]
	v_add_f32_e32 v70, v70, v71
	v_fmamk_f32 v70, v70, 0x3b000000, v1
	v_rsq_f32_e32 v70, v70
	s_nop 0
	v_pk_mul_f32 v[64:65], v[64:65], v[70:71] op_sel_hi:[1,0]
	v_pk_mul_f32 v[62:63], v[62:63], v[70:71] op_sel_hi:[1,0]
	v_pk_mul_f32 v[6:7], v[6:7], v[64:65]
	v_pk_mul_f32 v[8:9], v[8:9], v[62:63]
	v_cvt_pk_bf16_f32 v6, v6, v7
	v_cvt_pk_bf16_f32 v7, v8, v9
	v_and_b32_e32 v222, 32, v0
	v_lshrrev_b32_e32 v222, 2, v222
	v_mov_b32_e32 v223, 0
	v_lshl_add_u64 v[220:221], v[72:73], 0, v[222:223]
	v_lshl_add_u64 v[220:221], v[220:221], 0, v[238:239]
	v_mov_b32_e32 v202, v6
	v_mov_b32_e32 v203, v7
	v_pk_mul_f32 v[6:7], v[60:61], v[70:71] op_sel_hi:[1,0]
	s_nop 0
	v_pk_mul_f32 v[2:3], v[2:3], v[6:7]
	v_pk_mul_f32 v[6:7], v[58:59], v[70:71] op_sel_hi:[1,0]
	v_cvt_pk_bf16_f32 v2, v2, v3
	v_pk_mul_f32 v[4:5], v[4:5], v[6:7]
	s_nop 0
	v_cvt_pk_bf16_f32 v3, v4, v5
	v_mov_b32_e32 v204, v2
	v_mov_b32_e32 v205, v3
	s_nop 1
	v_permlane32_swap_b32_e32 v202, v204
	v_permlane32_swap_b32_e32 v203, v205
	ds_bpermute_b32 v202, v236, v202
	ds_bpermute_b32 v203, v236, v203
	ds_bpermute_b32 v204, v236, v204
	ds_bpermute_b32 v205, v236, v205
	s_waitcnt lgkmcnt(4)
; #define LAS __attribute__((address_space(3)))
; __device__ __forceinline__ unsigned pk2(float lo, float hi) { f32x2 v = {lo, hi}; bf16x2_t b = __builtin_convertvector(v, bf16x2_t); return __builtin_bit_cast(unsigned, b); }
; __device__ __forceinline__ void gmlp_unit(const GmlpP& P, int b, int ch, LAS unsigned char* lds, int wave, int lane_in) {
;     ...
; #pragma unroll
;     for (int nt = 0; nt < 2; ++nt) {
;         const int t = 32 * (nt == 0 ? tt0 : tt1) + r32;
;         const float tot = (ssqg[t] + ssqg[128 + t]) + (ssqg[256 + t] + ssqg[384 + t]);
;         const float r = __builtin_amdgcn_rsqf(tot * (1.0f / GW) + EPS);
;         bf16_t* op = P.MIX + (tok0 + t) * DM + AW + gI * 128 + 4 * h;
; #pragma unroll
;         for (int mt = 0; mt < 4; ++mt)
; #pragma unroll
;             for (int e4 = 0; e4 < 4; ++e4) {
;                 const f32x4 gg = *(const LAS f32x4*)(lds + LDS_GG + (gI * 128 + 32 * mt + 8 * e4 + 4 * h) * 4);
;                 u32x2 w; w.x = pk2(acc[mt][nt][4 * e4] * r * gg[0], acc[mt][nt][4 * e4 + 1] * r * gg[1]); w.y = pk2(acc[mt][nt][4 * e4 + 2] * r * gg[2], acc[mt][nt][4 * e4 + 3] * r * gg[3]);
;                 *(u32x2*)(op + 32 * mt + 8 * e4) = w;
;             }
;     }
; __global__ void __launch_bounds__(512, 2) mk_fwd(Args args) {
;     ...
;         for (int a = bx; a < 256 * REP_GM; a += G) gmlp_unit(GP, (a & 255) >> 4, a & 15, lds, wave, lane);
	global_store_dwordx4 v[218:219], v[214:217], off offset:1248
	v_pk_mul_f32 v[2:3], v[56:57], v[70:71] op_sel_hi:[1,0]
	v_pk_mul_f32 v[4:5], v[54:55], v[70:71] op_sel_hi:[1,0]
	v_pk_mul_f32 v[2:3], v[10:11], v[2:3]
	v_pk_mul_f32 v[4:5], v[12:13], v[4:5]
	v_cvt_pk_bf16_f32 v2, v2, v3
	v_cvt_pk_bf16_f32 v3, v4, v5
	v_mov_b32_e32 v206, v2
	v_mov_b32_e32 v207, v3
	v_pk_mul_f32 v[2:3], v[52:53], v[70:71] op_sel_hi:[1,0]
	v_pk_mul_f32 v[4:5], v[50:51], v[70:71] op_sel_hi:[1,0]
	v_pk_mul_f32 v[2:3], v[114:115], v[2:3]
	v_pk_mul_f32 v[4:5], v[116:117], v[4:5]
	v_cvt_pk_bf16_f32 v2, v2, v3
	v_cvt_pk_bf16_f32 v3, v4, v5
	v_mov_b32_e32 v208, v2
	v_mov_b32_e32 v209, v3
	s_nop 1
	v_permlane32_swap_b32_e32 v206, v208
	v_permlane32_swap_b32_e32 v207, v209
	ds_bpermute_b32 v206, v236, v206
	ds_bpermute_b32 v207, v236, v207
	ds_bpermute_b32 v208, v236, v208
	ds_bpermute_b32 v209, v236, v209
	s_waitcnt lgkmcnt(4)
	global_store_dwordx4 v[220:221], v[202:205], off offset:1024
	v_pk_mul_f32 v[2:3], v[36:37], v[70:71] op_sel_hi:[1,0]
	v_pk_mul_f32 v[4:5], v[34:35], v[70:71] op_sel_hi:[1,0]
	v_pk_mul_f32 v[2:3], v[118:119], v[2:3]
	v_pk_mul_f32 v[4:5], v[120:121], v[4:5]
	v_cvt_pk_bf16_f32 v2, v2, v3
	v_cvt_pk_bf16_f32 v3, v4, v5
	v_mov_b32_e32 v210, v2
	v_mov_b32_e32 v211, v3
	v_pk_mul_f32 v[2:3], v[38:39], v[70:71] op_sel_hi:[1,0]
	v_pk_mul_f32 v[4:5], v[40:41], v[70:71] op_sel_hi:[1,0]
	v_pk_mul_f32 v[2:3], v[122:123], v[2:3]
	v_pk_mul_f32 v[4:5], v[124:125], v[4:5]
	v_cvt_pk_bf16_f32 v2, v2, v3
	v_cvt_pk_bf16_f32 v3, v4, v5
	v_mov_b32_e32 v212, v2
	v_mov_b32_e32 v213, v3
	s_nop 1
	v_permlane32_swap_b32_e32 v210, v212
	v_permlane32_swap_b32_e32 v211, v213
	ds_bpermute_b32 v210, v236, v210
	ds_bpermute_b32 v211, v236, v211
	ds_bpermute_b32 v212, v236, v212
	ds_bpermute_b32 v213, v236, v213
	s_waitcnt lgkmcnt(4)
	global_store_dwordx4 v[220:221], v[206:209], off offset:1056
	v_pk_mul_f32 v[2:3], v[42:43], v[70:71] op_sel_hi:[1,0]
	v_pk_mul_f32 v[4:5], v[44:45], v[70:71] op_sel_hi:[1,0]
	v_pk_mul_f32 v[2:3], v[98:99], v[2:3]
	v_pk_mul_f32 v[4:5], v[100:101], v[4:5]
	v_cvt_pk_bf16_f32 v2, v2, v3
	v_cvt_pk_bf16_f32 v3, v4, v5
	v_mov_b32_e32 v214, v2
	v_mov_b32_e32 v215, v3
	v_pk_mul_f32 v[2:3], v[46:47], v[70:71] op_sel_hi:[1,0]
	v_pk_mul_f32 v[4:5], v[48:49], v[70:71] op_sel_hi:[1,0]
	v_pk_mul_f32 v[2:3], v[126:127], v[2:3]
	v_pk_mul_f32 v[4:5], v[128:129], v[4:5]
	v_cvt_pk_bf16_f32 v2, v2, v3
	v_cvt_pk_bf16_f32 v3, v4, v5
	v_mov_b32_e32 v216, v2
	v_mov_b32_e32 v217, v3
	s_nop 1
	v_permlane32_swap_b32_e32 v214, v216
	v_permlane32_swap_b32_e32 v215, v217
	ds_bpermute_b32 v214, v236, v214
	ds_bpermute_b32 v215, v236, v215
	ds_bpermute_b32 v216, v236, v216
	ds_bpermute_b32 v217, v236, v217
	s_waitcnt lgkmcnt(4)
	global_store_dwordx4 v[220:221], v[210:213], off offset:1088
	v_pk_mul_f32 v[2:3], v[18:19], v[70:71] op_sel_hi:[1,0]
	v_pk_mul_f32 v[4:5], v[20:21], v[70:71] op_sel_hi:[1,0]
	v_pk_mul_f32 v[2:3], v[102:103], v[2:3]
	v_pk_mul_f32 v[4:5], v[104:105], v[4:5]
	v_cvt_pk_bf16_f32 v2, v2, v3
	v_cvt_pk_bf16_f32 v3, v4, v5
	v_mov_b32_e32 v202, v2
	v_mov_b32_e32 v203, v3
	v_pk_mul_f32 v[2:3], v[22:23], v[70:71] op_sel_hi:[1,0]
	v_pk_mul_f32 v[4:5], v[24:25], v[70:71] op_sel_hi:[1,0]
	v_pk_mul_f32 v[2:3], v[106:107], v[2:3]
	v_pk_mul_f32 v[4:5], v[108:109], v[4:5]
	v_cvt_pk_bf16_f32 v2, v2, v3
	v_cvt_pk_bf16_f32 v3, v4, v5
	v_mov_b32_e32 v204, v2
	v_mov_b32_e32 v205, v3
	s_nop 1
	v_permlane32_swap_b32_e32 v202, v204
	v_permlane32_swap_b32_e32 v203, v205
	ds_bpermute_b32 v202, v236, v202
	ds_bpermute_b32 v203, v236, v203
	ds_bpermute_b32 v204, v236, v204
	ds_bpermute_b32 v205, v236, v205
	s_waitcnt lgkmcnt(4)
	global_store_dwordx4 v[220:221], v[214:217], off offset:1120
	v_pk_mul_f32 v[2:3], v[26:27], v[70:71] op_sel_hi:[1,0]
	v_pk_mul_f32 v[4:5], v[28:29], v[70:71] op_sel_hi:[1,0]
	v_pk_mul_f32 v[2:3], v[82:83], v[2:3]
	v_pk_mul_f32 v[4:5], v[84:85], v[4:5]
	v_cvt_pk_bf16_f32 v2, v2, v3
	v_cvt_pk_bf16_f32 v3, v4, v5
	v_mov_b32_e32 v206, v2
	v_mov_b32_e32 v207, v3
	v_pk_mul_f32 v[2:3], v[30:31], v[70:71] op_sel_hi:[1,0]
	v_pk_mul_f32 v[4:5], v[32:33], v[70:71] op_sel_hi:[1,0]
	v_pk_mul_f32 v[2:3], v[110:111], v[2:3]
	v_pk_mul_f32 v[4:5], v[112:113], v[4:5]
	v_cvt_pk_bf16_f32 v2, v2, v3
	v_cvt_pk_bf16_f32 v3, v4, v5
	v_mov_b32_e32 v208, v2
	v_mov_b32_e32 v209, v3
	s_nop 1
	v_permlane32_swap_b32_e32 v206, v208
	v_permlane32_swap_b32_e32 v207, v209
	ds_bpermute_b32 v206, v236, v206
	ds_bpermute_b32 v207, v236, v207
	ds_bpermute_b32 v208, v236, v208
	ds_bpermute_b32 v209, v236, v209
	s_waitcnt lgkmcnt(4)
	global_store_dwordx4 v[220:221], v[202:205], off offset:1152
	v_pk_mul_f32 v[2:3], v[80:81], v[70:71] op_sel_hi:[1,0]
	v_pk_mul_f32 v[4:5], v[132:133], v[70:71] op_sel_hi:[1,0]
	v_pk_mul_f32 v[2:3], v[86:87], v[2:3]
	v_pk_mul_f32 v[4:5], v[88:89], v[4:5]
	v_cvt_pk_bf16_f32 v2, v2, v3
	v_cvt_pk_bf16_f32 v3, v4, v5
	v_mov_b32_e32 v210, v2
	v_mov_b32_e32 v211, v3
	v_pk_mul_f32 v[2:3], v[134:135], v[70:71] op_sel_hi:[1,0]
	v_pk_mul_f32 v[4:5], v[136:137], v[70:71] op_sel_hi:[1,0]
	v_pk_mul_f32 v[2:3], v[90:91], v[2:3]
	v_pk_mul_f32 v[4:5], v[92:93], v[4:5]
	v_cvt_pk_bf16_f32 v2, v2, v3
	v_cvt_pk_bf16_f32 v3, v4, v5
	v_mov_b32_e32 v212, v2
	v_mov_b32_e32 v213, v3
	s_nop 1
	v_permlane32_swap_b32_e32 v210, v212
	v_permlane32_swap_b32_e32 v211, v213
	ds_bpermute_b32 v210, v236, v210
	ds_bpermute_b32 v211, v236, v211
	ds_bpermute_b32 v212, v236, v212
	ds_bpermute_b32 v213, v236, v213
	s_waitcnt lgkmcnt(4)
	global_store_dwordx4 v[220:221], v[206:209], off offset:1184
	v_pk_mul_f32 v[2:3], v[146:147], v[70:71] op_sel_hi:[1,0]
	v_pk_mul_f32 v[4:5], v[148:149], v[70:71] op_sel_hi:[1,0]
	v_pk_mul_f32 v[2:3], v[66:67], v[2:3]
	v_pk_mul_f32 v[4:5], v[68:69], v[4:5]
	v_cvt_pk_bf16_f32 v2, v2, v3
	v_cvt_pk_bf16_f32 v3, v4, v5
	v_mov_b32_e32 v214, v2
	v_mov_b32_e32 v215, v3
	v_pk_mul_f32 v[2:3], v[14:15], v[70:71] op_sel_hi:[1,0]
	v_pk_mul_f32 v[4:5], v[16:17], v[70:71] op_sel_hi:[1,0]
	v_pk_mul_f32 v[2:3], v[94:95], v[2:3]
	v_pk_mul_f32 v[4:5], v[96:97], v[4:5]
	v_cvt_pk_bf16_f32 v2, v2, v3
	v_cvt_pk_bf16_f32 v3, v4, v5
	v_mov_b32_e32 v216, v2
	v_mov_b32_e32 v217, v3
	s_nop 1
	v_permlane32_swap_b32_e32 v214, v216
	v_permlane32_swap_b32_e32 v215, v217
	ds_bpermute_b32 v214, v236, v214
	ds_bpermute_b32 v215, v236, v215
	ds_bpermute_b32 v216, v236, v216
	ds_bpermute_b32 v217, v236, v217
	s_waitcnt lgkmcnt(4)
	global_store_dwordx4 v[220:221], v[210:213], off offset:1216
	s_waitcnt lgkmcnt(0)
	global_store_dwordx4 v[220:221], v[214:217], off offset:1248
	s_cbranch_scc1 .LBB0_545

; __device__ __forceinline__ void gmlp_unit(const GmlpP& P, int b, int ch, LAS unsigned char* lds, int wave, int lane_in) {
;     ...
;             for (int i = 0; i < 8; ++i) {
;                 const u32x4 raw = rawv[8 * hf + i];
;                 float v[8];
; #pragma unroll
;                 for (int j = 0; j < 4; ++j) { v[2 * j] = __builtin_bit_cast(float, raw[j] << 16); v[2 * j + 1] = __builtin_bit_cast(float, raw[j] & 0xffff0000u); }
;                 float sm = 0.f;
; #pragma unroll
;                 for (int j = 0; j < 8; ++j) sm += v[j];
;                 sm = row16_sum(sm);
;                 const float mu = sm * (1.0f / 128.0f);
;                 float sq = 0.f;
; #pragma unroll
;                 for (int j = 0; j < 8; ++j) { v[j] -= mu; sq += v[j] * v[j]; }
;                 sq = row16_sum(sq);
;                 const float rs = __builtin_amdgcn_rsqf(sq * (1.0f / 128.0f) + EPS);
; #pragma unroll
;                 for (int j = 0; j < 8; ++j) yv[j][i] = v[j] * rs * (j < 4 ? ga0[j & 3] : ga1[j & 3]) + (j < 4 ? be0[j & 3] : be1[j & 3]);
;             }
.LBB0_541:
	s_or_b64 exec, exec, s[26:27]
	v_add_u32_e32 v109, s20, v86
	s_waitcnt vmcnt(14)
	v_lshlrev_b32_e32 v87, 16, v78
	v_lshlrev_b32_e32 v86, 16, v74
	s_waitcnt vmcnt(0)
	v_and_b32_e32 v82, 0xffff0000, v77
	v_lshlrev_b32_e32 v85, 16, v81
	v_lshlrev_b32_e32 v84, 16, v77
	v_and_b32_e32 v83, 0xffff0000, v81
	v_and_b32_e32 v89, 0xffff0000, v78
	v_and_b32_e32 v88, 0xffff0000, v74
	v_lshlrev_b32_e32 v90, 16, v75
	v_and_b32_e32 v78, 0xffff0000, v75
	v_lshlrev_b32_e32 v75, 16, v80
	v_and_b32_e32 v77, 0xffff0000, v80
	v_pk_add_f32 v[80:81], v[86:87], 0 op_sel_hi:[1,0]
	v_lshlrev_b32_e32 v91, 16, v79
	v_pk_add_f32 v[80:81], v[80:81], v[88:89]
	v_and_b32_e32 v79, 0xffff0000, v79
	v_pk_add_f32 v[80:81], v[80:81], v[90:91]
	v_lshlrev_b32_e32 v74, 16, v76
	v_pk_add_f32 v[80:81], v[80:81], v[78:79]
	v_and_b32_e32 v76, 0xffff0000, v76
	v_pk_add_f32 v[80:81], v[80:81], v[74:75]
	v_mov_b32_e32 v98, v82
	v_pk_add_f32 v[80:81], v[80:81], v[76:77]
	v_mov_b32_e32 v99, v84
	v_pk_add_f32 v[80:81], v[80:81], v[84:85]
	v_mov_b32_e32 v84, v83
	v_pk_add_f32 v[80:81], v[80:81], v[82:83]
	v_mov_b32_e32 v94, v76
	v_mov_b32_e32 v95, v74
	v_mov_b32_dpp v92, v80 row_ror:8 row_mask:0xf bank_mask:0xf bound_ctrl:1
	v_mov_b32_dpp v93, v81 row_ror:8 row_mask:0xf bank_mask:0xf bound_ctrl:1
	v_pk_add_f32 v[80:81], v[80:81], v[92:93]
	v_mov_b32_e32 v74, v77
	v_lshlrev_b32_e32 v106, 3, v108
	v_mov_b32_dpp v92, v80 row_ror:4 row_mask:0xf bank_mask:0xf bound_ctrl:1
	v_mov_b32_dpp v93, v81 row_ror:4 row_mask:0xf bank_mask:0xf bound_ctrl:1
	v_pk_add_f32 v[80:81], v[80:81], v[92:93]
	v_lshlrev_b32_e32 v107, 16, v71
	v_and_b32_e32 v71, 0xffff0000, v71
	v_mov_b32_dpp v92, v80 quad_perm:[2,3,0,1] row_mask:0xf bank_mask:0xf bound_ctrl:1
	v_mov_b32_dpp v93, v81 quad_perm:[2,3,0,1] row_mask:0xf bank_mask:0xf bound_ctrl:1
	v_pk_add_f32 v[80:81], v[80:81], v[92:93]
	v_lshlrev_b32_e32 v124, 16, v63
	v_lshlrev_b32_e32 v125, 16, v59
	v_mov_b32_dpp v92, v80 quad_perm:[1,0,3,2] row_mask:0xf bank_mask:0xf bound_ctrl:1
	v_mov_b32_dpp v93, v81 quad_perm:[1,0,3,2] row_mask:0xf bank_mask:0xf bound_ctrl:1
	v_pk_add_f32 v[80:81], v[80:81], v[92:93]
	v_and_b32_e32 v59, 0xffff0000, v59
	v_pk_mul_f32 v[92:93], v[80:81], s[24:25] op_sel_hi:[1,0]
	v_pk_fma_f32 v[82:83], v[80:81], s[24:25], v[88:89] op_sel_hi:[1,0,1] neg_lo:[1,0,0] neg_hi:[1,0,0]
	v_pk_fma_f32 v[86:87], v[80:81], s[24:25], v[86:87] op_sel_hi:[1,0,1] neg_lo:[1,0,0] neg_hi:[1,0,0]
	v_pk_add_f32 v[104:105], v[84:85], v[92:93] op_sel:[0,1] neg_lo:[0,1] neg_hi:[0,1]
	v_pk_mul_f32 v[84:85], v[82:83], v[82:83]
	v_pk_fma_f32 v[88:89], v[80:81], s[24:25], v[90:91] op_sel_hi:[1,0,1] neg_lo:[1,0,0] neg_hi:[1,0,0]
	v_pk_fma_f32 v[84:85], v[86:87], v[86:87], v[84:85]
	v_pk_add_f32 v[96:97], v[94:95], v[92:93] op_sel_hi:[1,0] neg_lo:[0,1] neg_hi:[0,1]
	v_pk_add_f32 v[102:103], v[74:75], v[92:93] op_sel:[0,1] neg_lo:[0,1] neg_hi:[0,1]
	v_pk_fma_f32 v[84:85], v[88:89], v[88:89], v[84:85]
	v_pk_fma_f32 v[78:79], v[80:81], s[24:25], v[78:79] op_sel_hi:[1,0,1] neg_lo:[1,0,0] neg_hi:[1,0,0]
	v_pk_mul_f32 v[94:95], v[96:97], v[96:97]
	v_pk_mul_f32 v[74:75], v[102:103], v[102:103]
	v_pk_fma_f32 v[80:81], v[78:79], v[78:79], v[84:85]
	v_pk_add_f32 v[98:99], v[98:99], v[92:93] op_sel_hi:[1,0] neg_lo:[0,1] neg_hi:[0,1]
	v_add_f32_e32 v80, v95, v80
	v_add_f32_e32 v75, v75, v81
	v_pk_mul_f32 v[100:101], v[98:99], v[98:99]
	v_pk_mul_f32 v[76:77], v[104:105], v[104:105]
	v_add_f32_e32 v80, v94, v80
	v_add_f32_e32 v74, v74, v75
	v_add_f32_e32 v80, v101, v80
	v_add_f32_e32 v74, v77, v74
	v_add_f32_e32 v80, v100, v80
	v_add_f32_e32 v74, v76, v74
	v_and_b32_e32 v154, 31, v139
	v_add_f32_dpp v80, v80, v80 row_ror:8 row_mask:0xf bank_mask:0xf bound_ctrl:1
	v_add_f32_dpp v74, v74, v74 row_ror:8 row_mask:0xf bank_mask:0xf bound_ctrl:1
	v_ashrrev_i32_e32 v140, 5, v139
	v_add_f32_dpp v80, v80, v80 row_ror:4 row_mask:0xf bank_mask:0xf bound_ctrl:1
	v_add_f32_dpp v74, v74, v74 row_ror:4 row_mask:0xf bank_mask:0xf bound_ctrl:1
	v_bfe_u32 v188, v139, 3, 2
	v_add_f32_dpp v80, v80, v80 quad_perm:[2,3,0,1] row_mask:0xf bank_mask:0xf bound_ctrl:1
	v_add_f32_dpp v74, v74, v74 quad_perm:[2,3,0,1] row_mask:0xf bank_mask:0xf bound_ctrl:1
	v_add_u32_e32 v152, 2, v140
	v_add_f32_dpp v80, v80, v80 quad_perm:[1,0,3,2] row_mask:0xf bank_mask:0xf bound_ctrl:1
	v_add_f32_dpp v74, v74, v74 quad_perm:[1,0,3,2] row_mask:0xf bank_mask:0xf bound_ctrl:1
	v_fmamk_f32 v80, v80, 0x3c000000, v1
	v_fmamk_f32 v74, v74, 0x3c000000, v1
	v_rsq_f32_e32 v100, v80
	v_rsq_f32_e32 v101, v74
	v_or_b32_e32 v74, s6, v106
	v_mul_lo_u32 v74, v74, s48
	v_add_u32_e32 v75, 0, v74
	v_pk_mul_f32 v[76:77], v[86:87], v[100:101]
	v_pk_mul_f32 v[78:79], v[78:79], v[100:101]
	v_pk_fma_f32 v[94:95], v[10:11], v[76:77], v[14:15] op_sel_hi:[0,1,0]
	v_pk_mul_f32 v[76:77], v[82:83], v[100:101]
	v_mov_b32_e32 v74, v13
	v_pk_fma_f32 v[92:93], v[10:11], v[76:77], v[14:15] op_sel:[1,0,1]
	v_pk_mul_f32 v[76:77], v[88:89], v[100:101]
	v_mov_b32_e32 v80, v7
	v_pk_fma_f32 v[90:91], v[12:13], v[76:77], v[16:17] op_sel_hi:[0,1,0]
	v_mov_b32_e32 v76, v17
	v_pk_fma_f32 v[88:89], v[74:75], v[78:79], v[76:77] op_sel_hi:[0,1,0]
	v_mov_b32_e32 v78, v97
	v_mov_b32_e32 v79, v103
	v_pk_mul_f32 v[78:79], v[78:79], v[100:101]
	v_mov_b32_e32 v97, v102
	v_pk_fma_f32 v[86:87], v[2:3], v[78:79], v[6:7] op_sel_hi:[0,1,0]
	v_pk_mul_f32 v[82:83], v[96:97], v[100:101]
	v_mov_b32_e32 v78, v3
	v_pk_fma_f32 v[84:85], v[78:79], v[82:83], v[80:81] op_sel_hi:[0,1,0]
	v_mov_b32_e32 v82, v99
	v_mov_b32_e32 v83, v105
	v_mov_b32_e32 v99, v104
	v_lshlrev_b32_e32 v103, 16, v70
	v_lshlrev_b32_e32 v102, 16, v66
	v_pk_mul_f32 v[82:83], v[82:83], v[100:101]
; __device__ __forceinline__ void gmlp_unit(const GmlpP& P, int b, int ch, LAS unsigned char* lds, int wave, int lane_in) {
;     ...
;             for (int i = 0; i < 8; ++i) {
;                 const u32x4 raw = rawv[8 * hf + i];
;                 float v[8];
; #pragma unroll
;                 for (int j = 0; j < 4; ++j) { v[2 * j] = __builtin_bit_cast(float, raw[j] << 16); v[2 * j + 1] = __builtin_bit_cast(float, raw[j] & 0xffff0000u); }
;                 float sm = 0.f;
; #pragma unroll
;                 for (int j = 0; j < 8; ++j) sm += v[j];
;                 sm = row16_sum(sm);
;                 const float mu = sm * (1.0f / 128.0f);
;                 float sq = 0.f;
; #pragma unroll
;                 for (int j = 0; j < 8; ++j) { v[j] -= mu; sq += v[j] * v[j]; }
;                 sq = row16_sum(sq);
;                 const float rs = __builtin_amdgcn_rsqf(sq * (1.0f / 128.0f) + EPS);
; #pragma unroll
;                 for (int j = 0; j < 8; ++j) yv[j][i] = v[j] * rs * (j < 4 ? ga0[j & 3] : ga1[j & 3]) + (j < 4 ? be0[j & 3] : be1[j & 3]);
;             }
	v_pk_mul_f32 v[96:97], v[98:99], v[100:101]
	v_and_b32_e32 v98, 0xffff0000, v69
	v_lshlrev_b32_e32 v101, 16, v73
	v_lshlrev_b32_e32 v100, 16, v69
	v_and_b32_e32 v99, 0xffff0000, v73
	v_and_b32_e32 v105, 0xffff0000, v70
	v_and_b32_e32 v104, 0xffff0000, v66
	v_lshlrev_b32_e32 v106, 16, v67
	v_and_b32_e32 v70, 0xffff0000, v67
	v_lshlrev_b32_e32 v67, 16, v72
	v_and_b32_e32 v69, 0xffff0000, v72
	v_pk_add_f32 v[72:73], v[102:103], 0 op_sel_hi:[1,0]
	v_lshlrev_b32_e32 v66, 16, v68
	v_pk_add_f32 v[72:73], v[72:73], v[104:105]
	v_and_b32_e32 v68, 0xffff0000, v68
	v_pk_add_f32 v[72:73], v[72:73], v[106:107]
	v_mov_b32_e32 v112, v68
	v_pk_add_f32 v[72:73], v[72:73], v[70:71]
	v_mov_b32_e32 v113, v66
	v_pk_add_f32 v[72:73], v[72:73], v[66:67]
	v_mov_b32_e32 v116, v98
	v_pk_add_f32 v[72:73], v[72:73], v[68:69]
	v_mov_b32_e32 v117, v100
	v_pk_add_f32 v[72:73], v[72:73], v[100:101]
	v_mov_b32_e32 v66, v69
	v_pk_add_f32 v[72:73], v[72:73], v[98:99]
	v_mov_b32_e32 v100, v99
	v_pk_fma_f32 v[82:83], v[4:5], v[82:83], v[8:9] op_sel_hi:[0,1,0]
	v_mov_b32_dpp v110, v72 row_ror:8 row_mask:0xf bank_mask:0xf bound_ctrl:1
	v_mov_b32_dpp v111, v73 row_ror:8 row_mask:0xf bank_mask:0xf bound_ctrl:1
	v_pk_add_f32 v[72:73], v[72:73], v[110:111]
	v_xor_b32_e32 v153, v188, v152
	v_cmp_gt_u32_e32 vcc, 32, v139
	v_mov_b32_dpp v110, v72 row_ror:4 row_mask:0xf bank_mask:0xf bound_ctrl:1
	v_mov_b32_dpp v111, v73 row_ror:4 row_mask:0xf bank_mask:0xf bound_ctrl:1
	v_pk_add_f32 v[72:73], v[72:73], v[110:111]
	s_nop 1
	v_mov_b32_dpp v110, v72 quad_perm:[2,3,0,1] row_mask:0xf bank_mask:0xf bound_ctrl:1
	v_mov_b32_dpp v111, v73 quad_perm:[2,3,0,1] row_mask:0xf bank_mask:0xf bound_ctrl:1
	v_pk_add_f32 v[72:73], v[72:73], v[110:111]
	s_nop 1
	v_mov_b32_dpp v110, v72 quad_perm:[1,0,3,2] row_mask:0xf bank_mask:0xf bound_ctrl:1
	v_mov_b32_dpp v111, v73 quad_perm:[1,0,3,2] row_mask:0xf bank_mask:0xf bound_ctrl:1
	v_pk_add_f32 v[72:73], v[72:73], v[110:111]
	s_nop 0
	v_pk_mul_f32 v[110:111], v[72:73], s[24:25] op_sel_hi:[1,0]
	v_pk_fma_f32 v[98:99], v[72:73], s[24:25], v[104:105] op_sel_hi:[1,0,1] neg_lo:[1,0,0] neg_hi:[1,0,0]
	v_pk_fma_f32 v[102:103], v[72:73], s[24:25], v[102:103] op_sel_hi:[1,0,1] neg_lo:[1,0,0] neg_hi:[1,0,0]
	v_pk_add_f32 v[112:113], v[112:113], v[110:111] op_sel_hi:[1,0] neg_lo:[0,1] neg_hi:[0,1]
	v_pk_add_f32 v[116:117], v[116:117], v[110:111] op_sel_hi:[1,0] neg_lo:[0,1] neg_hi:[0,1]
	v_pk_add_f32 v[120:121], v[66:67], v[110:111] op_sel:[0,1] neg_lo:[0,1] neg_hi:[0,1]
	v_pk_add_f32 v[110:111], v[100:101], v[110:111] op_sel:[0,1] neg_lo:[0,1] neg_hi:[0,1]
	v_pk_mul_f32 v[100:101], v[98:99], v[98:99]
	v_pk_fma_f32 v[122:123], v[72:73], s[24:25], v[106:107] op_sel_hi:[1,0,1] neg_lo:[1,0,0] neg_hi:[1,0,0]
	v_pk_fma_f32 v[100:101], v[102:103], v[102:103], v[100:101]
	v_pk_fma_f32 v[72:73], v[72:73], s[24:25], v[70:71] op_sel_hi:[1,0,1] neg_lo:[1,0,0] neg_hi:[1,0,0]
	v_pk_fma_f32 v[100:101], v[122:123], v[122:123], v[100:101]
	v_pk_mul_f32 v[114:115], v[112:113], v[112:113]
	v_pk_fma_f32 v[70:71], v[72:73], v[72:73], v[100:101]
	v_pk_mul_f32 v[118:119], v[116:117], v[116:117]
	v_add_f32_e32 v3, v115, v70
	v_add_f32_e32 v3, v114, v3
	v_add_f32_e32 v3, v119, v3
	v_add_f32_e32 v3, v118, v3
	v_pk_mul_f32 v[66:67], v[120:121], v[120:121]
	v_pk_mul_f32 v[68:69], v[110:111], v[110:111]
	v_add_f32_dpp v3, v3, v3 row_ror:8 row_mask:0xf bank_mask:0xf bound_ctrl:1
	v_lshlrev_b32_e32 v119, 16, v61
	v_lshlrev_b32_e32 v118, 16, v65
	v_add_f32_dpp v3, v3, v3 row_ror:4 row_mask:0xf bank_mask:0xf bound_ctrl:1
	v_mov_b32_e32 v133, v118
	s_nop 0
	v_add_f32_dpp v3, v3, v3 quad_perm:[2,3,0,1] row_mask:0xf bank_mask:0xf bound_ctrl:1
	s_nop 1
	v_add_f32_dpp v3, v3, v3 quad_perm:[1,0,3,2] row_mask:0xf bank_mask:0xf bound_ctrl:1
	v_fmamk_f32 v3, v3, 0x3c000000, v1
	v_rsq_f32_e32 v114, v3
	v_add_f32_e32 v3, v67, v71
	v_add_f32_e32 v3, v66, v3
	v_add_f32_e32 v3, v69, v3
	v_add_f32_e32 v3, v68, v3
	v_mov_b32_e32 v66, v5
	v_mov_b32_e32 v68, v9
	v_add_f32_dpp v3, v3, v3 row_ror:8 row_mask:0xf bank_mask:0xf bound_ctrl:1
	v_pk_fma_f32 v[70:71], v[66:67], v[96:97], v[68:69] op_sel_hi:[0,1,0]
	s_nop 0
	v_add_f32_dpp v3, v3, v3 row_ror:4 row_mask:0xf bank_mask:0xf bound_ctrl:1
	s_nop 1
	v_add_f32_dpp v3, v3, v3 quad_perm:[2,3,0,1] row_mask:0xf bank_mask:0xf bound_ctrl:1
	s_nop 1
	v_add_f32_dpp v3, v3, v3 quad_perm:[1,0,3,2] row_mask:0xf bank_mask:0xf bound_ctrl:1
	v_fmamk_f32 v3, v3, 0x3c000000, v1
	v_rsq_f32_e32 v115, v3
	s_nop 0
	v_pk_mul_f32 v[72:73], v[72:73], v[114:115]
	v_pk_mul_f32 v[96:97], v[102:103], v[114:115]
	v_pk_fma_f32 v[100:101], v[74:75], v[72:73], v[76:77] op_sel_hi:[0,1,0]
	v_mov_b32_e32 v72, v113
	v_mov_b32_e32 v73, v121
	v_pk_fma_f32 v[106:107], v[10:11], v[96:97], v[14:15] op_sel_hi:[0,1,0]
	v_pk_mul_f32 v[96:97], v[98:99], v[114:115]
	v_pk_mul_f32 v[72:73], v[72:73], v[114:115]
	v_mov_b32_e32 v113, v120
	v_lshlrev_b32_e32 v121, 16, v58
	v_lshlrev_b32_e32 v120, 16, v62
	v_pk_fma_f32 v[104:105], v[10:11], v[96:97], v[14:15] op_sel:[1,0,1]
	v_pk_mul_f32 v[96:97], v[122:123], v[114:115]
	v_pk_fma_f32 v[98:99], v[2:3], v[72:73], v[6:7] op_sel_hi:[0,1,0]
	v_pk_mul_f32 v[72:73], v[112:113], v[114:115]
	v_and_b32_e32 v112, 0xffff0000, v65
	v_and_b32_e32 v113, 0xffff0000, v61
	v_and_b32_e32 v123, 0xffff0000, v58
	v_and_b32_e32 v122, 0xffff0000, v62
	v_and_b32_e32 v58, 0xffff0000, v63
	v_lshlrev_b32_e32 v63, 16, v60
	v_lshlrev_b32_e32 v62, 16, v64
	v_and_b32_e32 v61, 0xffff0000, v60
	v_and_b32_e32 v60, 0xffff0000, v64
	v_pk_add_f32 v[64:65], v[120:121], 0 op_sel_hi:[1,0]
	v_mov_b32_e32 v128, v60
	v_pk_add_f32 v[64:65], v[64:65], v[122:123]
	v_mov_b32_e32 v129, v62
; __device__ __forceinline__ void gmlp_unit(const GmlpP& P, int b, int ch, LAS unsigned char* lds, int wave, int lane_in) {
;     ...
;             for (int i = 0; i < 8; ++i) {
;                 const u32x4 raw = rawv[8 * hf + i];
;                 float v[8];
; #pragma unroll
;                 for (int j = 0; j < 4; ++j) { v[2 * j] = __builtin_bit_cast(float, raw[j] << 16); v[2 * j + 1] = __builtin_bit_cast(float, raw[j] & 0xffff0000u); }
;                 float sm = 0.f;
; #pragma unroll
;                 for (int j = 0; j < 8; ++j) sm += v[j];
;                 sm = row16_sum(sm);
;                 const float mu = sm * (1.0f / 128.0f);
;                 float sq = 0.f;
; #pragma unroll
;                 for (int j = 0; j < 8; ++j) { v[j] -= mu; sq += v[j] * v[j]; }
;                 sq = row16_sum(sq);
;                 const float rs = __builtin_amdgcn_rsqf(sq * (1.0f / 128.0f) + EPS);
; #pragma unroll
;                 for (int j = 0; j < 8; ++j) yv[j][i] = v[j] * rs * (j < 4 ? ga0[j & 3] : ga1[j & 3]) + (j < 4 ? be0[j & 3] : be1[j & 3]);
;             }
	v_pk_add_f32 v[64:65], v[64:65], v[124:125]
	v_mov_b32_e32 v132, v112
	v_pk_add_f32 v[64:65], v[64:65], v[58:59]
	v_pk_fma_f32 v[102:103], v[12:13], v[96:97], v[16:17] op_sel_hi:[0,1,0]
	v_pk_add_f32 v[64:65], v[64:65], v[62:63]
	v_mov_b32_e32 v62, v61
	v_pk_add_f32 v[64:65], v[64:65], v[60:61]
	v_pk_fma_f32 v[96:97], v[78:79], v[72:73], v[80:81] op_sel_hi:[0,1,0]
	v_pk_add_f32 v[64:65], v[64:65], v[118:119]
	v_mov_b32_e32 v118, v113
	v_pk_add_f32 v[64:65], v[64:65], v[112:113]
	v_mov_b32_e32 v72, v117
	v_mov_b32_e32 v73, v111
	v_mov_b32_dpp v126, v64 row_ror:8 row_mask:0xf bank_mask:0xf bound_ctrl:1
	v_mov_b32_dpp v127, v65 row_ror:8 row_mask:0xf bank_mask:0xf bound_ctrl:1
	v_pk_add_f32 v[64:65], v[64:65], v[126:127]
	v_mov_b32_e32 v117, v110
	v_pk_mul_f32 v[72:73], v[72:73], v[114:115]
	v_mov_b32_dpp v126, v64 row_ror:4 row_mask:0xf bank_mask:0xf bound_ctrl:1
	v_mov_b32_dpp v127, v65 row_ror:4 row_mask:0xf bank_mask:0xf bound_ctrl:1
	v_pk_add_f32 v[64:65], v[64:65], v[126:127]
	v_pk_fma_f32 v[72:73], v[4:5], v[72:73], v[8:9] op_sel_hi:[0,1,0]
	s_nop 0
	v_mov_b32_dpp v126, v64 quad_perm:[2,3,0,1] row_mask:0xf bank_mask:0xf bound_ctrl:1
	v_mov_b32_dpp v127, v65 quad_perm:[2,3,0,1] row_mask:0xf bank_mask:0xf bound_ctrl:1
	v_pk_add_f32 v[64:65], v[64:65], v[126:127]
	s_nop 1
	v_mov_b32_dpp v126, v64 quad_perm:[1,0,3,2] row_mask:0xf bank_mask:0xf bound_ctrl:1
	v_mov_b32_dpp v127, v65 quad_perm:[1,0,3,2] row_mask:0xf bank_mask:0xf bound_ctrl:1
	v_pk_add_f32 v[64:65], v[64:65], v[126:127]
	s_nop 0
	v_pk_mul_f32 v[126:127], v[64:65], s[24:25] op_sel_hi:[1,0]
	v_pk_fma_f32 v[122:123], v[64:65], s[24:25], v[122:123] op_sel_hi:[1,0,1] neg_lo:[1,0,0] neg_hi:[1,0,0]
	v_pk_fma_f32 v[120:121], v[64:65], s[24:25], v[120:121] op_sel_hi:[1,0,1] neg_lo:[1,0,0] neg_hi:[1,0,0]
	v_pk_add_f32 v[128:129], v[128:129], v[126:127] op_sel_hi:[1,0] neg_lo:[0,1] neg_hi:[0,1]
	v_pk_add_f32 v[132:133], v[132:133], v[126:127] op_sel_hi:[1,0] neg_lo:[0,1] neg_hi:[0,1]
	v_pk_add_f32 v[60:61], v[62:63], v[126:127] op_sel:[0,1] neg_lo:[0,1] neg_hi:[0,1]
	v_pk_add_f32 v[112:113], v[118:119], v[126:127] op_sel:[0,1] neg_lo:[0,1] neg_hi:[0,1]
	v_pk_mul_f32 v[126:127], v[122:123], v[122:123]
	v_pk_fma_f32 v[124:125], v[64:65], s[24:25], v[124:125] op_sel_hi:[1,0,1] neg_lo:[1,0,0] neg_hi:[1,0,0]
	v_pk_fma_f32 v[126:127], v[120:121], v[120:121], v[126:127]
	v_pk_fma_f32 v[58:59], v[64:65], s[24:25], v[58:59] op_sel_hi:[1,0,1] neg_lo:[1,0,0] neg_hi:[1,0,0]
	v_pk_fma_f32 v[126:127], v[124:125], v[124:125], v[126:127]
	v_pk_mul_f32 v[130:131], v[128:129], v[128:129]
	v_pk_fma_f32 v[64:65], v[58:59], v[58:59], v[126:127]
	v_pk_mul_f32 v[134:135], v[132:133], v[132:133]
	v_add_f32_e32 v3, v131, v64
	v_add_f32_e32 v3, v130, v3
	v_add_f32_e32 v3, v135, v3
	v_add_f32_e32 v3, v134, v3
	v_pk_mul_f32 v[62:63], v[60:61], v[60:61]
	v_pk_mul_f32 v[118:119], v[112:113], v[112:113]
	v_add_f32_dpp v3, v3, v3 row_ror:8 row_mask:0xf bank_mask:0xf bound_ctrl:1
	v_lshlrev_b32_e32 v127, 16, v54
	v_lshlrev_b32_e32 v126, 16, v50
	v_add_f32_dpp v3, v3, v3 row_ror:4 row_mask:0xf bank_mask:0xf bound_ctrl:1
	v_lshlrev_b32_e32 v130, 16, v51
	v_lshlrev_b32_e32 v131, 16, v55
	v_add_f32_dpp v3, v3, v3 quad_perm:[2,3,0,1] row_mask:0xf bank_mask:0xf bound_ctrl:1
	v_and_b32_e32 v55, 0xffff0000, v55
	s_nop 0
	v_add_f32_dpp v3, v3, v3 quad_perm:[1,0,3,2] row_mask:0xf bank_mask:0xf bound_ctrl:1
	v_fmamk_f32 v3, v3, 0x3c000000, v1
	v_rsq_f32_e32 v64, v3
	v_add_f32_e32 v3, v63, v65
	v_add_f32_e32 v3, v62, v3
	v_add_f32_e32 v3, v119, v3
	v_add_f32_e32 v3, v118, v3
	v_mov_b32_e32 v118, v129
	v_mov_b32_e32 v129, v60
	v_add_f32_dpp v3, v3, v3 row_ror:8 row_mask:0xf bank_mask:0xf bound_ctrl:1
	v_pk_mul_f32 v[62:63], v[116:117], v[114:115]
	v_mov_b32_e32 v119, v61
	v_add_f32_dpp v3, v3, v3 row_ror:4 row_mask:0xf bank_mask:0xf bound_ctrl:1
	v_pk_fma_f32 v[62:63], v[66:67], v[62:63], v[68:69] op_sel_hi:[0,1,0]
	s_nop 0
	v_add_f32_dpp v3, v3, v3 quad_perm:[2,3,0,1] row_mask:0xf bank_mask:0xf bound_ctrl:1
	s_nop 1
	v_add_f32_dpp v3, v3, v3 quad_perm:[1,0,3,2] row_mask:0xf bank_mask:0xf bound_ctrl:1
	v_fmamk_f32 v3, v3, 0x3c000000, v1
	v_rsq_f32_e32 v65, v3
	s_nop 0
	v_pk_mul_f32 v[114:115], v[122:123], v[64:65]
	v_pk_mul_f32 v[116:117], v[124:125], v[64:65]
	v_pk_mul_f32 v[60:61], v[128:129], v[64:65]
	v_and_b32_e32 v122, 0xffff0000, v53
	v_lshlrev_b32_e32 v125, 16, v57
	v_lshlrev_b32_e32 v124, 16, v53
	v_and_b32_e32 v123, 0xffff0000, v57
	v_and_b32_e32 v129, 0xffff0000, v54
	v_and_b32_e32 v128, 0xffff0000, v50
	v_and_b32_e32 v54, 0xffff0000, v51
	v_lshlrev_b32_e32 v51, 16, v56
	v_and_b32_e32 v53, 0xffff0000, v56
	v_pk_add_f32 v[56:57], v[126:127], 0 op_sel_hi:[1,0]
	v_lshlrev_b32_e32 v50, 16, v52
	v_pk_add_f32 v[56:57], v[56:57], v[128:129]
	v_and_b32_e32 v52, 0xffff0000, v52
	v_pk_add_f32 v[56:57], v[56:57], v[130:131]
	v_mov_b32_e32 v136, v52
	v_pk_add_f32 v[56:57], v[56:57], v[54:55]
	v_mov_b32_e32 v137, v50
	v_pk_add_f32 v[56:57], v[56:57], v[50:51]
	v_mov_b32_e32 v146, v122
	v_pk_add_f32 v[56:57], v[56:57], v[52:53]
	v_mov_b32_e32 v147, v124
	v_pk_add_f32 v[56:57], v[56:57], v[124:125]
	v_mov_b32_e32 v50, v53
	v_pk_add_f32 v[56:57], v[56:57], v[122:123]
	v_mov_b32_e32 v124, v123
	v_pk_mul_f32 v[118:119], v[118:119], v[64:65]
	v_mov_b32_dpp v134, v56 row_ror:8 row_mask:0xf bank_mask:0xf bound_ctrl:1
	v_mov_b32_dpp v135, v57 row_ror:8 row_mask:0xf bank_mask:0xf bound_ctrl:1
	v_pk_add_f32 v[56:57], v[56:57], v[134:135]
	v_pk_fma_f32 v[118:119], v[2:3], v[118:119], v[6:7] op_sel_hi:[0,1,0]
	v_pk_mul_f32 v[110:111], v[120:121], v[64:65]
	v_mov_b32_dpp v134, v56 row_ror:4 row_mask:0xf bank_mask:0xf bound_ctrl:1
; #define LAS __attribute__((address_space(3)))
; __device__ __forceinline__ unsigned pk2(float lo, float hi) { f32x2 v = {lo, hi}; bf16x2_t b = __builtin_convertvector(v, bf16x2_t); return __builtin_bit_cast(unsigned, b); }
; __device__ __forceinline__ void gmlp_unit(const GmlpP& P, int b, int ch, LAS unsigned char* lds, int wave, int lane_in) {
;     ...
;             for (int i = 0; i < 8; ++i) {
;                 const u32x4 raw = rawv[8 * hf + i];
;                 float v[8];
; #pragma unroll
;                 for (int j = 0; j < 4; ++j) { v[2 * j] = __builtin_bit_cast(float, raw[j] << 16); v[2 * j + 1] = __builtin_bit_cast(float, raw[j] & 0xffff0000u); }
;                 float sm = 0.f;
; #pragma unroll
;                 for (int j = 0; j < 8; ++j) sm += v[j];
;                 sm = row16_sum(sm);
;                 const float mu = sm * (1.0f / 128.0f);
;                 float sq = 0.f;
; #pragma unroll
;                 for (int j = 0; j < 8; ++j) { v[j] -= mu; sq += v[j] * v[j]; }
;                 sq = row16_sum(sq);
;                 const float rs = __builtin_amdgcn_rsqf(sq * (1.0f / 128.0f) + EPS);
; #pragma unroll
;                 for (int j = 0; j < 8; ++j) yv[j][i] = v[j] * rs * (j < 4 ? ga0[j & 3] : ga1[j & 3]) + (j < 4 ? be0[j & 3] : be1[j & 3]);
;             }
;             const int s0 = 64 * th + 16 * rr + 8 * hf;
;             LAS unsigned char* dst = lds + (gI * 128 + 8 * sub) * LDS_TT_PITCH + 16 * ((s0 >> 3) ^ sub);
; #pragma unroll
;             for (int j = 0; j < 8; ++j) {
;                 u32x4 w; w.x = pk2(yv[j][0], yv[j][1]); w.y = pk2(yv[j][2], yv[j][3]); w.z = pk2(yv[j][4], yv[j][5]); w.w = pk2(yv[j][6], yv[j][7]);
;                 *(LAS u32x4*)(dst + j * LDS_TT_PITCH) = w;
;             }
	v_mov_b32_dpp v135, v57 row_ror:4 row_mask:0xf bank_mask:0xf bound_ctrl:1
	v_pk_add_f32 v[56:57], v[56:57], v[134:135]
	v_mov_b32_e32 v120, v133
	v_mov_b32_e32 v133, v112
	v_mov_b32_dpp v134, v56 quad_perm:[2,3,0,1] row_mask:0xf bank_mask:0xf bound_ctrl:1
	v_mov_b32_dpp v135, v57 quad_perm:[2,3,0,1] row_mask:0xf bank_mask:0xf bound_ctrl:1
	v_pk_add_f32 v[56:57], v[56:57], v[134:135]
	v_mov_b32_e32 v121, v113
	v_pk_mul_f32 v[58:59], v[58:59], v[64:65]
	v_mov_b32_dpp v134, v56 quad_perm:[1,0,3,2] row_mask:0xf bank_mask:0xf bound_ctrl:1
	v_mov_b32_dpp v135, v57 quad_perm:[1,0,3,2] row_mask:0xf bank_mask:0xf bound_ctrl:1
	v_pk_add_f32 v[56:57], v[56:57], v[134:135]
	v_pk_mul_f32 v[120:121], v[120:121], v[64:65]
	v_pk_mul_f32 v[134:135], v[56:57], s[24:25] op_sel_hi:[1,0]
	v_pk_fma_f32 v[128:129], v[56:57], s[24:25], v[128:129] op_sel_hi:[1,0,1] neg_lo:[1,0,0] neg_hi:[1,0,0]
	v_pk_fma_f32 v[126:127], v[56:57], s[24:25], v[126:127] op_sel_hi:[1,0,1] neg_lo:[1,0,0] neg_hi:[1,0,0]
	v_pk_add_f32 v[136:137], v[136:137], v[134:135] op_sel_hi:[1,0] neg_lo:[0,1] neg_hi:[0,1]
	v_pk_add_f32 v[146:147], v[146:147], v[134:135] op_sel_hi:[1,0] neg_lo:[0,1] neg_hi:[0,1]
	v_pk_add_f32 v[50:51], v[50:51], v[134:135] op_sel:[0,1] neg_lo:[0,1] neg_hi:[0,1]
	v_pk_add_f32 v[122:123], v[124:125], v[134:135] op_sel:[0,1] neg_lo:[0,1] neg_hi:[0,1]
	v_pk_mul_f32 v[134:135], v[128:129], v[128:129]
	v_pk_fma_f32 v[130:131], v[56:57], s[24:25], v[130:131] op_sel_hi:[1,0,1] neg_lo:[1,0,0] neg_hi:[1,0,0]
	v_pk_fma_f32 v[134:135], v[126:127], v[126:127], v[134:135]
	v_pk_fma_f32 v[54:55], v[56:57], s[24:25], v[54:55] op_sel_hi:[1,0,1] neg_lo:[1,0,0] neg_hi:[1,0,0]
	v_pk_fma_f32 v[134:135], v[130:131], v[130:131], v[134:135]
	v_pk_mul_f32 v[144:145], v[136:137], v[136:137]
	v_pk_fma_f32 v[56:57], v[54:55], v[54:55], v[134:135]
	v_pk_mul_f32 v[148:149], v[146:147], v[146:147]
	v_add_f32_e32 v3, v145, v56
	v_add_f32_e32 v3, v144, v3
	v_add_f32_e32 v3, v149, v3
	v_add_f32_e32 v3, v148, v3
	v_pk_mul_f32 v[52:53], v[50:51], v[50:51]
	v_pk_mul_f32 v[124:125], v[122:123], v[122:123]
	v_add_f32_dpp v3, v3, v3 row_ror:8 row_mask:0xf bank_mask:0xf bound_ctrl:1
	v_pk_fma_f32 v[110:111], v[10:11], v[110:111], v[14:15] op_sel_hi:[0,1,0]
	v_pk_fma_f32 v[120:121], v[4:5], v[120:121], v[8:9] op_sel_hi:[0,1,0]
	v_add_f32_dpp v3, v3, v3 row_ror:4 row_mask:0xf bank_mask:0xf bound_ctrl:1
	v_pk_fma_f32 v[114:115], v[10:11], v[114:115], v[14:15] op_sel:[1,0,1]
	v_pk_fma_f32 v[116:117], v[12:13], v[116:117], v[16:17] op_sel_hi:[0,1,0]
	v_add_f32_dpp v3, v3, v3 quad_perm:[2,3,0,1] row_mask:0xf bank_mask:0xf bound_ctrl:1
	v_pk_fma_f32 v[58:59], v[74:75], v[58:59], v[76:77] op_sel_hi:[0,1,0]
	v_pk_fma_f32 v[60:61], v[78:79], v[60:61], v[80:81] op_sel_hi:[0,1,0]
	v_add_f32_dpp v3, v3, v3 quad_perm:[1,0,3,2] row_mask:0xf bank_mask:0xf bound_ctrl:1
	v_fmamk_f32 v3, v3, 0x3c000000, v1
	v_rsq_f32_e32 v56, v3
	v_add_f32_e32 v3, v53, v57
	v_add_f32_e32 v3, v52, v3
	v_add_f32_e32 v3, v125, v3
	v_add_f32_e32 v3, v124, v3
	v_pk_mul_f32 v[52:53], v[132:133], v[64:65]
	s_nop 0
	v_add_f32_dpp v3, v3, v3 row_ror:8 row_mask:0xf bank_mask:0xf bound_ctrl:1
	v_pk_fma_f32 v[64:65], v[66:67], v[52:53], v[68:69] op_sel_hi:[0,1,0]
	s_nop 0
	v_add_f32_dpp v3, v3, v3 row_ror:4 row_mask:0xf bank_mask:0xf bound_ctrl:1
	s_nop 1
	v_add_f32_dpp v3, v3, v3 quad_perm:[2,3,0,1] row_mask:0xf bank_mask:0xf bound_ctrl:1
	s_nop 1
	v_add_f32_dpp v3, v3, v3 quad_perm:[1,0,3,2] row_mask:0xf bank_mask:0xf bound_ctrl:1
	v_fmamk_f32 v3, v3, 0x3c000000, v1
	v_rsq_f32_e32 v57, v3
	s_nop 0
	v_pk_mul_f32 v[52:53], v[126:127], v[56:57]
	s_nop 0
	v_pk_fma_f32 v[112:113], v[10:11], v[52:53], v[14:15] op_sel_hi:[0,1,0]
	v_pk_mul_f32 v[52:53], v[128:129], v[56:57]
	s_nop 0
	v_pk_fma_f32 v[124:125], v[10:11], v[52:53], v[14:15] op_sel:[1,0,1]
	v_pk_mul_f32 v[52:53], v[130:131], v[56:57]
	s_nop 0
	v_pk_fma_f32 v[126:127], v[12:13], v[52:53], v[16:17] op_sel_hi:[0,1,0]
	v_pk_mul_f32 v[52:53], v[54:55], v[56:57]
	s_nop 0
	v_pk_fma_f32 v[54:55], v[74:75], v[52:53], v[76:77] op_sel_hi:[0,1,0]
	v_mov_b32_e32 v52, v137
	v_mov_b32_e32 v137, v50
	v_mov_b32_e32 v53, v51
	v_pk_mul_f32 v[50:51], v[136:137], v[56:57]
	v_pk_mul_f32 v[52:53], v[52:53], v[56:57]
	v_pk_fma_f32 v[130:131], v[78:79], v[50:51], v[80:81] op_sel_hi:[0,1,0]
	v_mov_b32_e32 v50, v147
	v_mov_b32_e32 v51, v123
	v_pk_fma_f32 v[128:129], v[2:3], v[52:53], v[6:7] op_sel_hi:[0,1,0]
	v_pk_mul_f32 v[50:51], v[50:51], v[56:57]
	v_mov_b32_e32 v147, v122
	v_ashrrev_i32_e32 v3, 3, v109
	v_pk_fma_f32 v[132:133], v[4:5], v[50:51], v[8:9] op_sel_hi:[0,1,0]
	v_pk_mul_f32 v[50:51], v[146:147], v[56:57]
	v_xor_b32_e32 v5, v3, v108
	v_pk_fma_f32 v[56:57], v[66:67], v[50:51], v[68:69] op_sel_hi:[0,1,0]
	v_lshl_add_u32 v5, v5, 4, v75
	v_cvt_pk_bf16_f32 v50, v94, v95
	v_cvt_pk_bf16_f32 v51, v106, v107
	v_cvt_pk_bf16_f32 v52, v110, v111
	v_cvt_pk_bf16_f32 v53, v112, v113
	ds_write_b128 v5, v[50:53]
	v_cvt_pk_bf16_f32 v50, v92, v93
	v_cvt_pk_bf16_f32 v51, v104, v105
	v_cvt_pk_bf16_f32 v52, v114, v115
	v_cvt_pk_bf16_f32 v53, v124, v125
	ds_write_b128 v5, v[50:53] offset:272
	v_cvt_pk_bf16_f32 v50, v90, v91
	v_cvt_pk_bf16_f32 v51, v102, v103
	v_cvt_pk_bf16_f32 v52, v116, v117
	v_cvt_pk_bf16_f32 v53, v126, v127
	ds_write_b128 v5, v[50:53] offset:544
	v_cvt_pk_bf16_f32 v50, v88, v89
	v_cvt_pk_bf16_f32 v51, v100, v101
	v_cvt_pk_bf16_f32 v52, v58, v59
	v_cvt_pk_bf16_f32 v53, v54, v55
	ds_write_b128 v5, v[50:53] offset:816
	v_cvt_pk_bf16_f32 v50, v86, v87
	v_cvt_pk_bf16_f32 v51, v98, v99
	v_cvt_pk_bf16_f32 v52, v118, v119
	v_cvt_pk_bf16_f32 v53, v128, v129
	ds_write_b128 v5, v[50:53] offset:1088
	v_cvt_pk_bf16_f32 v50, v84, v85
; #define LAS __attribute__((address_space(3)))
; __device__ __forceinline__ unsigned pk2(float lo, float hi) { f32x2 v = {lo, hi}; bf16x2_t b = __builtin_convertvector(v, bf16x2_t); return __builtin_bit_cast(unsigned, b); }
; __device__ __forceinline__ void gmlp_unit(const GmlpP& P, int b, int ch, LAS unsigned char* lds, int wave, int lane_in) {
;     ...
;             for (int i = 0; i < 8; ++i) {
;                 const u32x4 raw = rawv[8 * hf + i];
;                 float v[8];
; #pragma unroll
;                 for (int j = 0; j < 4; ++j) { v[2 * j] = __builtin_bit_cast(float, raw[j] << 16); v[2 * j + 1] = __builtin_bit_cast(float, raw[j] & 0xffff0000u); }
;                 float sm = 0.f;
; #pragma unroll
;                 for (int j = 0; j < 8; ++j) sm += v[j];
;                 sm = row16_sum(sm);
;                 const float mu = sm * (1.0f / 128.0f);
;                 float sq = 0.f;
; #pragma unroll
;                 for (int j = 0; j < 8; ++j) { v[j] -= mu; sq += v[j] * v[j]; }
;                 sq = row16_sum(sq);
;                 const float rs = __builtin_amdgcn_rsqf(sq * (1.0f / 128.0f) + EPS);
; #pragma unroll
;                 for (int j = 0; j < 8; ++j) yv[j][i] = v[j] * rs * (j < 4 ? ga0[j & 3] : ga1[j & 3]) + (j < 4 ? be0[j & 3] : be1[j & 3]);
;             }
;             const int s0 = 64 * th + 16 * rr + 8 * hf;
;             LAS unsigned char* dst = lds + (gI * 128 + 8 * sub) * LDS_TT_PITCH + 16 * ((s0 >> 3) ^ sub);
; #pragma unroll
;             for (int j = 0; j < 8; ++j) {
;                 u32x4 w; w.x = pk2(yv[j][0], yv[j][1]); w.y = pk2(yv[j][2], yv[j][3]); w.z = pk2(yv[j][4], yv[j][5]); w.w = pk2(yv[j][6], yv[j][7]);
;                 *(LAS u32x4*)(dst + j * LDS_TT_PITCH) = w;
;             }
	v_cvt_pk_bf16_f32 v51, v96, v97
	v_cvt_pk_bf16_f32 v52, v60, v61
	v_cvt_pk_bf16_f32 v53, v130, v131
	ds_write_b128 v5, v[50:53] offset:1360
	v_cvt_pk_bf16_f32 v50, v82, v83
	v_cvt_pk_bf16_f32 v51, v72, v73
	v_cvt_pk_bf16_f32 v52, v120, v121
	v_cvt_pk_bf16_f32 v53, v132, v133
	v_lshlrev_b32_e32 v61, 16, v46
	v_lshlrev_b32_e32 v60, 16, v42
	ds_write_b128 v5, v[50:53] offset:1632
	v_cvt_pk_bf16_f32 v51, v62, v63
	v_cvt_pk_bf16_f32 v52, v64, v65
	v_and_b32_e32 v54, 0xffff0000, v45
	v_lshlrev_b32_e32 v59, 16, v49
	v_lshlrev_b32_e32 v58, 16, v45
	v_and_b32_e32 v55, 0xffff0000, v49
	v_and_b32_e32 v63, 0xffff0000, v46
	v_and_b32_e32 v62, 0xffff0000, v42
	v_lshlrev_b32_e32 v64, 16, v43
	v_and_b32_e32 v46, 0xffff0000, v43
	v_lshlrev_b32_e32 v43, 16, v48
	v_and_b32_e32 v45, 0xffff0000, v48
	v_pk_add_f32 v[48:49], v[60:61], 0 op_sel_hi:[1,0]
	v_lshlrev_b32_e32 v65, 16, v47
	v_pk_add_f32 v[48:49], v[48:49], v[62:63]
	v_and_b32_e32 v47, 0xffff0000, v47
	v_pk_add_f32 v[48:49], v[48:49], v[64:65]
	v_lshlrev_b32_e32 v42, 16, v44
	v_pk_add_f32 v[48:49], v[48:49], v[46:47]
	v_and_b32_e32 v44, 0xffff0000, v44
	v_pk_add_f32 v[48:49], v[48:49], v[42:43]
	v_cvt_pk_bf16_f32 v50, v70, v71
	v_pk_add_f32 v[48:49], v[48:49], v[44:45]
	v_mov_b32_e32 v72, v44
	v_pk_add_f32 v[48:49], v[48:49], v[58:59]
	v_mov_b32_e32 v73, v42
	v_pk_add_f32 v[48:49], v[48:49], v[54:55]
	v_mov_b32_e32 v84, v54
	v_mov_b32_e32 v85, v58
	v_mov_b32_dpp v70, v48 row_ror:8 row_mask:0xf bank_mask:0xf bound_ctrl:1
	v_mov_b32_dpp v71, v49 row_ror:8 row_mask:0xf bank_mask:0xf bound_ctrl:1
	v_pk_add_f32 v[48:49], v[48:49], v[70:71]
	v_mov_b32_e32 v42, v45
	v_mov_b32_e32 v58, v55
	v_mov_b32_dpp v70, v48 row_ror:4 row_mask:0xf bank_mask:0xf bound_ctrl:1
	v_mov_b32_dpp v71, v49 row_ror:4 row_mask:0xf bank_mask:0xf bound_ctrl:1
	v_pk_add_f32 v[48:49], v[48:49], v[70:71]
	v_cvt_pk_bf16_f32 v53, v56, v57
	ds_write_b128 v5, v[50:53] offset:1904
	v_mov_b32_dpp v70, v48 quad_perm:[2,3,0,1] row_mask:0xf bank_mask:0xf bound_ctrl:1
	v_mov_b32_dpp v71, v49 quad_perm:[2,3,0,1] row_mask:0xf bank_mask:0xf bound_ctrl:1
	v_pk_add_f32 v[48:49], v[48:49], v[70:71]
	v_and_b32_e32 v56, 0xffff0000, v37
	v_and_b32_e32 v57, 0xffff0000, v41
	v_mov_b32_dpp v70, v48 quad_perm:[1,0,3,2] row_mask:0xf bank_mask:0xf bound_ctrl:1
	v_mov_b32_dpp v71, v49 quad_perm:[1,0,3,2] row_mask:0xf bank_mask:0xf bound_ctrl:1
	v_pk_add_f32 v[48:49], v[48:49], v[70:71]
	v_mov_b32_e32 v90, v56
	v_pk_mul_f32 v[70:71], v[48:49], s[24:25] op_sel_hi:[1,0]
	v_pk_fma_f32 v[62:63], v[48:49], s[24:25], v[62:63] op_sel_hi:[1,0,1] neg_lo:[1,0,0] neg_hi:[1,0,0]
	v_pk_fma_f32 v[60:61], v[48:49], s[24:25], v[60:61] op_sel_hi:[1,0,1] neg_lo:[1,0,0] neg_hi:[1,0,0]
	v_pk_add_f32 v[72:73], v[72:73], v[70:71] op_sel_hi:[1,0] neg_lo:[0,1] neg_hi:[0,1]
	v_pk_add_f32 v[84:85], v[84:85], v[70:71] op_sel_hi:[1,0] neg_lo:[0,1] neg_hi:[0,1]
	v_pk_add_f32 v[42:43], v[42:43], v[70:71] op_sel:[0,1] neg_lo:[0,1] neg_hi:[0,1]
	v_pk_add_f32 v[58:59], v[58:59], v[70:71] op_sel:[0,1] neg_lo:[0,1] neg_hi:[0,1]
	v_pk_mul_f32 v[70:71], v[62:63], v[62:63]
	v_pk_fma_f32 v[64:65], v[48:49], s[24:25], v[64:65] op_sel_hi:[1,0,1] neg_lo:[1,0,0] neg_hi:[1,0,0]
	v_pk_fma_f32 v[70:71], v[60:61], v[60:61], v[70:71]
	v_pk_fma_f32 v[46:47], v[48:49], s[24:25], v[46:47] op_sel_hi:[1,0,1] neg_lo:[1,0,0] neg_hi:[1,0,0]
	v_pk_fma_f32 v[70:71], v[64:65], v[64:65], v[70:71]
	v_pk_mul_f32 v[82:83], v[72:73], v[72:73]
	v_pk_fma_f32 v[48:49], v[46:47], v[46:47], v[70:71]
	v_pk_mul_f32 v[86:87], v[84:85], v[84:85]
	v_add_f32_e32 v7, v83, v48
	v_add_f32_e32 v7, v82, v7
	v_add_f32_e32 v7, v87, v7
	v_add_f32_e32 v7, v86, v7
	v_pk_mul_f32 v[44:45], v[42:43], v[42:43]
	v_pk_mul_f32 v[54:55], v[58:59], v[58:59]
	v_add_f32_dpp v7, v7, v7 row_ror:8 row_mask:0xf bank_mask:0xf bound_ctrl:1
	s_nop 1
	v_add_f32_dpp v7, v7, v7 row_ror:4 row_mask:0xf bank_mask:0xf bound_ctrl:1
	s_nop 1
	v_add_f32_dpp v7, v7, v7 quad_perm:[2,3,0,1] row_mask:0xf bank_mask:0xf bound_ctrl:1
	s_nop 1
	v_add_f32_dpp v7, v7, v7 quad_perm:[1,0,3,2] row_mask:0xf bank_mask:0xf bound_ctrl:1
	v_fmamk_f32 v7, v7, 0x3c000000, v1
	v_rsq_f32_e32 v70, v7
	v_add_f32_e32 v7, v45, v49
	v_add_f32_e32 v7, v44, v7
	v_add_f32_e32 v7, v55, v7
	v_add_f32_e32 v7, v54, v7
	s_nop 1
	v_add_f32_dpp v7, v7, v7 row_ror:8 row_mask:0xf bank_mask:0xf bound_ctrl:1
	s_nop 1
	v_add_f32_dpp v7, v7, v7 row_ror:4 row_mask:0xf bank_mask:0xf bound_ctrl:1
	s_nop 1
	v_add_f32_dpp v7, v7, v7 quad_perm:[2,3,0,1] row_mask:0xf bank_mask:0xf bound_ctrl:1
	s_nop 1
	v_add_f32_dpp v7, v7, v7 quad_perm:[1,0,3,2] row_mask:0xf bank_mask:0xf bound_ctrl:1
	v_fmamk_f32 v7, v7, 0x3c000000, v1
	v_rsq_f32_e32 v71, v7
	s_nop 0
	v_pk_mul_f32 v[44:45], v[60:61], v[70:71]
	s_nop 0
	v_pk_fma_f32 v[54:55], v[10:11], v[44:45], v[14:15] op_sel_hi:[0,1,0]
	v_pk_mul_f32 v[44:45], v[62:63], v[70:71]
	v_lshlrev_b32_e32 v63, 16, v38
	v_pk_fma_f32 v[52:53], v[10:11], v[44:45], v[14:15] op_sel:[1,0,1]
	v_pk_mul_f32 v[44:45], v[64:65], v[70:71]
	v_lshlrev_b32_e32 v62, 16, v34
	v_pk_fma_f32 v[50:51], v[12:13], v[44:45], v[16:17] op_sel_hi:[0,1,0]
	v_pk_mul_f32 v[44:45], v[46:47], v[70:71]
	v_lshlrev_b32_e32 v61, 16, v41
	v_pk_fma_f32 v[48:49], v[74:75], v[44:45], v[76:77] op_sel_hi:[0,1,0]
	v_mov_b32_e32 v44, v73
	v_mov_b32_e32 v73, v42
	v_mov_b32_e32 v45, v43
	v_pk_mul_f32 v[42:43], v[72:73], v[70:71]
	v_lshlrev_b32_e32 v60, 16, v37
	v_and_b32_e32 v65, 0xffff0000, v38
	v_and_b32_e32 v64, 0xffff0000, v34
	v_lshlrev_b32_e32 v72, 16, v35
	v_and_b32_e32 v38, 0xffff0000, v35
	v_lshlrev_b32_e32 v35, 16, v40
	v_and_b32_e32 v37, 0xffff0000, v40
	v_pk_add_f32 v[40:41], v[62:63], 0 op_sel_hi:[1,0]
	v_lshlrev_b32_e32 v73, 16, v39
; __device__ __forceinline__ void gmlp_unit(const GmlpP& P, int b, int ch, LAS unsigned char* lds, int wave, int lane_in) {
;     ...
;             for (int i = 0; i < 8; ++i) {
;                 const u32x4 raw = rawv[8 * hf + i];
;                 float v[8];
; #pragma unroll
;                 for (int j = 0; j < 4; ++j) { v[2 * j] = __builtin_bit_cast(float, raw[j] << 16); v[2 * j + 1] = __builtin_bit_cast(float, raw[j] & 0xffff0000u); }
;                 float sm = 0.f;
; #pragma unroll
;                 for (int j = 0; j < 8; ++j) sm += v[j];
;                 sm = row16_sum(sm);
;                 const float mu = sm * (1.0f / 128.0f);
;                 float sq = 0.f;
; #pragma unroll
;                 for (int j = 0; j < 8; ++j) { v[j] -= mu; sq += v[j] * v[j]; }
;                 sq = row16_sum(sq);
;                 const float rs = __builtin_amdgcn_rsqf(sq * (1.0f / 128.0f) + EPS);
; #pragma unroll
;                 for (int j = 0; j < 8; ++j) yv[j][i] = v[j] * rs * (j < 4 ? ga0[j & 3] : ga1[j & 3]) + (j < 4 ? be0[j & 3] : be1[j & 3]);
;             }
	v_pk_add_f32 v[40:41], v[40:41], v[64:65]
	v_and_b32_e32 v39, 0xffff0000, v39
	v_pk_add_f32 v[40:41], v[40:41], v[72:73]
	v_lshlrev_b32_e32 v34, 16, v36
	v_pk_add_f32 v[40:41], v[40:41], v[38:39]
	v_and_b32_e32 v36, 0xffff0000, v36
	v_pk_add_f32 v[40:41], v[40:41], v[34:35]
	v_mov_b32_e32 v86, v36
	v_pk_add_f32 v[40:41], v[40:41], v[36:37]
	v_mov_b32_e32 v87, v34
	v_pk_add_f32 v[40:41], v[40:41], v[60:61]
	v_mov_b32_e32 v91, v60
	v_pk_add_f32 v[40:41], v[40:41], v[56:57]
	v_mov_b32_e32 v34, v37
	v_mov_b32_e32 v60, v57
	v_mov_b32_dpp v82, v40 row_ror:8 row_mask:0xf bank_mask:0xf bound_ctrl:1
	v_mov_b32_dpp v83, v41 row_ror:8 row_mask:0xf bank_mask:0xf bound_ctrl:1
	v_pk_add_f32 v[40:41], v[40:41], v[82:83]
	v_pk_mul_f32 v[44:45], v[44:45], v[70:71]
	s_nop 0
	v_mov_b32_dpp v82, v40 row_ror:4 row_mask:0xf bank_mask:0xf bound_ctrl:1
	v_mov_b32_dpp v83, v41 row_ror:4 row_mask:0xf bank_mask:0xf bound_ctrl:1
	v_pk_add_f32 v[40:41], v[40:41], v[82:83]
	v_pk_fma_f32 v[46:47], v[2:3], v[44:45], v[6:7] op_sel_hi:[0,1,0]
	v_pk_fma_f32 v[44:45], v[78:79], v[42:43], v[80:81] op_sel_hi:[0,1,0]
	v_mov_b32_dpp v82, v40 quad_perm:[2,3,0,1] row_mask:0xf bank_mask:0xf bound_ctrl:1
	v_mov_b32_dpp v83, v41 quad_perm:[2,3,0,1] row_mask:0xf bank_mask:0xf bound_ctrl:1
	v_pk_add_f32 v[40:41], v[40:41], v[82:83]
	v_mov_b32_e32 v42, v85
	v_mov_b32_e32 v43, v59
	v_mov_b32_dpp v82, v40 quad_perm:[1,0,3,2] row_mask:0xf bank_mask:0xf bound_ctrl:1
	v_mov_b32_dpp v83, v41 quad_perm:[1,0,3,2] row_mask:0xf bank_mask:0xf bound_ctrl:1
	v_pk_add_f32 v[40:41], v[40:41], v[82:83]
	v_pk_mul_f32 v[42:43], v[42:43], v[70:71]
	v_pk_mul_f32 v[82:83], v[40:41], s[24:25] op_sel_hi:[1,0]
	v_pk_fma_f32 v[62:63], v[40:41], s[24:25], v[62:63] op_sel_hi:[1,0,1] neg_lo:[1,0,0] neg_hi:[1,0,0]
	v_pk_add_f32 v[86:87], v[86:87], v[82:83] op_sel_hi:[1,0] neg_lo:[0,1] neg_hi:[0,1]
	v_pk_add_f32 v[90:91], v[90:91], v[82:83] op_sel_hi:[1,0] neg_lo:[0,1] neg_hi:[0,1]
	v_pk_add_f32 v[36:37], v[34:35], v[82:83] op_sel:[0,1] neg_lo:[0,1] neg_hi:[0,1]
	v_pk_add_f32 v[82:83], v[60:61], v[82:83] op_sel:[0,1] neg_lo:[0,1] neg_hi:[0,1]
	v_pk_fma_f32 v[60:61], v[40:41], s[24:25], v[64:65] op_sel_hi:[1,0,1] neg_lo:[1,0,0] neg_hi:[1,0,0]
	v_pk_fma_f32 v[72:73], v[40:41], s[24:25], v[72:73] op_sel_hi:[1,0,1] neg_lo:[1,0,0] neg_hi:[1,0,0]
	v_pk_mul_f32 v[64:65], v[60:61], v[60:61]
	v_pk_fma_f32 v[38:39], v[40:41], s[24:25], v[38:39] op_sel_hi:[1,0,1] neg_lo:[1,0,0] neg_hi:[1,0,0]
	v_pk_fma_f32 v[64:65], v[62:63], v[62:63], v[64:65]
	v_pk_mul_f32 v[88:89], v[86:87], v[86:87]
	v_pk_fma_f32 v[64:65], v[72:73], v[72:73], v[64:65]
	v_pk_fma_f32 v[42:43], v[4:5], v[42:43], v[8:9] op_sel_hi:[0,1,0]
	v_pk_fma_f32 v[40:41], v[38:39], v[38:39], v[64:65]
	v_pk_mul_f32 v[92:93], v[90:91], v[90:91]
	v_add_f32_e32 v5, v89, v40
	v_add_f32_e32 v5, v88, v5
	v_add_f32_e32 v5, v93, v5
	v_add_f32_e32 v5, v92, v5
	v_pk_mul_f32 v[34:35], v[36:37], v[36:37]
	v_pk_mul_f32 v[56:57], v[82:83], v[82:83]
	v_add_f32_dpp v5, v5, v5 row_ror:8 row_mask:0xf bank_mask:0xf bound_ctrl:1
	v_mov_b32_e32 v85, v58
	v_lshlrev_b32_e32 v88, 16, v27
	v_add_f32_dpp v5, v5, v5 row_ror:4 row_mask:0xf bank_mask:0xf bound_ctrl:1
	v_lshlrev_b32_e32 v89, 16, v31
	v_and_b32_e32 v31, 0xffff0000, v31
	v_add_f32_dpp v5, v5, v5 quad_perm:[2,3,0,1] row_mask:0xf bank_mask:0xf bound_ctrl:1
	s_nop 1
	v_add_f32_dpp v5, v5, v5 quad_perm:[1,0,3,2] row_mask:0xf bank_mask:0xf bound_ctrl:1
	v_fmamk_f32 v5, v5, 0x3c000000, v1
	v_rsq_f32_e32 v64, v5
	v_add_f32_e32 v5, v35, v41
	v_add_f32_e32 v5, v34, v5
	v_add_f32_e32 v5, v57, v5
	v_add_f32_e32 v5, v56, v5
	v_pk_mul_f32 v[34:35], v[84:85], v[70:71]
	v_lshlrev_b32_e32 v85, 16, v30
	v_add_f32_dpp v5, v5, v5 row_ror:8 row_mask:0xf bank_mask:0xf bound_ctrl:1
	v_lshlrev_b32_e32 v84, 16, v26
	v_and_b32_e32 v70, 0xffff0000, v29
	v_add_f32_dpp v5, v5, v5 row_ror:4 row_mask:0xf bank_mask:0xf bound_ctrl:1
	v_and_b32_e32 v71, 0xffff0000, v33
	v_mov_b32_e32 v98, v70
	v_add_f32_dpp v5, v5, v5 quad_perm:[2,3,0,1] row_mask:0xf bank_mask:0xf bound_ctrl:1
	v_pk_fma_f32 v[34:35], v[66:67], v[34:35], v[68:69] op_sel_hi:[0,1,0]
	s_nop 0
	v_add_f32_dpp v5, v5, v5 quad_perm:[1,0,3,2] row_mask:0xf bank_mask:0xf bound_ctrl:1
	v_fmamk_f32 v5, v5, 0x3c000000, v1
	v_rsq_f32_e32 v65, v5
	s_nop 0
	v_pk_mul_f32 v[40:41], v[62:63], v[64:65]
	v_pk_mul_f32 v[38:39], v[38:39], v[64:65]
	v_pk_fma_f32 v[62:63], v[10:11], v[40:41], v[14:15] op_sel_hi:[0,1,0]
	v_pk_mul_f32 v[40:41], v[60:61], v[64:65]
	v_pk_fma_f32 v[56:57], v[74:75], v[38:39], v[76:77] op_sel_hi:[0,1,0]
	v_mov_b32_e32 v38, v87
	v_mov_b32_e32 v87, v36
	v_pk_fma_f32 v[60:61], v[10:11], v[40:41], v[14:15] op_sel:[1,0,1]
	v_pk_mul_f32 v[40:41], v[72:73], v[64:65]
	v_mov_b32_e32 v39, v37
	v_pk_mul_f32 v[36:37], v[86:87], v[64:65]
	v_lshlrev_b32_e32 v73, 16, v33
	v_lshlrev_b32_e32 v72, 16, v29
	v_and_b32_e32 v87, 0xffff0000, v30
	v_and_b32_e32 v86, 0xffff0000, v26
	v_and_b32_e32 v30, 0xffff0000, v27
	v_lshlrev_b32_e32 v27, 16, v32
	v_and_b32_e32 v29, 0xffff0000, v32
	v_pk_add_f32 v[32:33], v[84:85], 0 op_sel_hi:[1,0]
	v_lshlrev_b32_e32 v26, 16, v28
	v_pk_add_f32 v[32:33], v[32:33], v[86:87]
	v_and_b32_e32 v28, 0xffff0000, v28
	v_pk_add_f32 v[32:33], v[32:33], v[88:89]
	v_mov_b32_e32 v94, v28
	v_pk_add_f32 v[32:33], v[32:33], v[30:31]
	v_mov_b32_e32 v95, v26
	v_pk_add_f32 v[32:33], v[32:33], v[26:27]
	v_mov_b32_e32 v99, v72
	v_pk_add_f32 v[32:33], v[32:33], v[28:29]
	v_mov_b32_e32 v26, v29
	v_pk_add_f32 v[32:33], v[32:33], v[72:73]
	v_mov_b32_e32 v72, v71
	v_pk_add_f32 v[32:33], v[32:33], v[70:71]
	v_pk_mul_f32 v[38:39], v[38:39], v[64:65]
	v_pk_fma_f32 v[58:59], v[12:13], v[40:41], v[16:17] op_sel_hi:[0,1,0]
; __device__ __forceinline__ void gmlp_unit(const GmlpP& P, int b, int ch, LAS unsigned char* lds, int wave, int lane_in) {
;     ...
;             for (int i = 0; i < 8; ++i) {
;                 const u32x4 raw = rawv[8 * hf + i];
;                 float v[8];
; #pragma unroll
;                 for (int j = 0; j < 4; ++j) { v[2 * j] = __builtin_bit_cast(float, raw[j] << 16); v[2 * j + 1] = __builtin_bit_cast(float, raw[j] & 0xffff0000u); }
;                 float sm = 0.f;
; #pragma unroll
;                 for (int j = 0; j < 8; ++j) sm += v[j];
;                 sm = row16_sum(sm);
;                 const float mu = sm * (1.0f / 128.0f);
;                 float sq = 0.f;
; #pragma unroll
;                 for (int j = 0; j < 8; ++j) { v[j] -= mu; sq += v[j] * v[j]; }
;                 sq = row16_sum(sq);
;                 const float rs = __builtin_amdgcn_rsqf(sq * (1.0f / 128.0f) + EPS);
; #pragma unroll
;                 for (int j = 0; j < 8; ++j) yv[j][i] = v[j] * rs * (j < 4 ? ga0[j & 3] : ga1[j & 3]) + (j < 4 ? be0[j & 3] : be1[j & 3]);
;             }
	v_mov_b32_dpp v92, v32 row_ror:8 row_mask:0xf bank_mask:0xf bound_ctrl:1
	v_mov_b32_dpp v93, v33 row_ror:8 row_mask:0xf bank_mask:0xf bound_ctrl:1
	v_pk_add_f32 v[32:33], v[32:33], v[92:93]
	v_pk_fma_f32 v[40:41], v[2:3], v[38:39], v[6:7] op_sel_hi:[0,1,0]
	v_pk_fma_f32 v[38:39], v[78:79], v[36:37], v[80:81] op_sel_hi:[0,1,0]
	v_mov_b32_dpp v92, v32 row_ror:4 row_mask:0xf bank_mask:0xf bound_ctrl:1
	v_mov_b32_dpp v93, v33 row_ror:4 row_mask:0xf bank_mask:0xf bound_ctrl:1
	v_pk_add_f32 v[32:33], v[32:33], v[92:93]
	v_mov_b32_e32 v36, v91
	v_mov_b32_e32 v37, v83
	v_mov_b32_dpp v92, v32 quad_perm:[2,3,0,1] row_mask:0xf bank_mask:0xf bound_ctrl:1
	v_mov_b32_dpp v93, v33 quad_perm:[2,3,0,1] row_mask:0xf bank_mask:0xf bound_ctrl:1
	v_pk_add_f32 v[32:33], v[32:33], v[92:93]
	v_pk_mul_f32 v[36:37], v[36:37], v[64:65]
	v_mov_b32_e32 v91, v82
	v_mov_b32_dpp v92, v32 quad_perm:[1,0,3,2] row_mask:0xf bank_mask:0xf bound_ctrl:1
	v_mov_b32_dpp v93, v33 quad_perm:[1,0,3,2] row_mask:0xf bank_mask:0xf bound_ctrl:1
	v_pk_add_f32 v[32:33], v[32:33], v[92:93]
	v_pk_fma_f32 v[36:37], v[4:5], v[36:37], v[8:9] op_sel_hi:[0,1,0]
	v_pk_mul_f32 v[92:93], v[32:33], s[24:25] op_sel_hi:[1,0]
	v_pk_fma_f32 v[86:87], v[32:33], s[24:25], v[86:87] op_sel_hi:[1,0,1] neg_lo:[1,0,0] neg_hi:[1,0,0]
	v_pk_fma_f32 v[84:85], v[32:33], s[24:25], v[84:85] op_sel_hi:[1,0,1] neg_lo:[1,0,0] neg_hi:[1,0,0]
	v_pk_add_f32 v[94:95], v[94:95], v[92:93] op_sel_hi:[1,0] neg_lo:[0,1] neg_hi:[0,1]
	v_pk_add_f32 v[98:99], v[98:99], v[92:93] op_sel_hi:[1,0] neg_lo:[0,1] neg_hi:[0,1]
	v_pk_add_f32 v[26:27], v[26:27], v[92:93] op_sel:[0,1] neg_lo:[0,1] neg_hi:[0,1]
	v_pk_add_f32 v[70:71], v[72:73], v[92:93] op_sel:[0,1] neg_lo:[0,1] neg_hi:[0,1]
	v_pk_mul_f32 v[92:93], v[86:87], v[86:87]
	v_pk_fma_f32 v[88:89], v[32:33], s[24:25], v[88:89] op_sel_hi:[1,0,1] neg_lo:[1,0,0] neg_hi:[1,0,0]
	v_pk_fma_f32 v[92:93], v[84:85], v[84:85], v[92:93]
	v_pk_fma_f32 v[30:31], v[32:33], s[24:25], v[30:31] op_sel_hi:[1,0,1] neg_lo:[1,0,0] neg_hi:[1,0,0]
	v_pk_fma_f32 v[92:93], v[88:89], v[88:89], v[92:93]
	v_pk_mul_f32 v[96:97], v[94:95], v[94:95]
	v_pk_fma_f32 v[32:33], v[30:31], v[30:31], v[92:93]
	v_pk_mul_f32 v[100:101], v[98:99], v[98:99]
	v_add_f32_e32 v5, v97, v32
	v_add_f32_e32 v5, v96, v5
	v_add_f32_e32 v5, v101, v5
	v_add_f32_e32 v5, v100, v5
	v_pk_mul_f32 v[28:29], v[26:27], v[26:27]
	v_pk_mul_f32 v[72:73], v[70:71], v[70:71]
	v_add_f32_dpp v5, v5, v5 row_ror:8 row_mask:0xf bank_mask:0xf bound_ctrl:1
	v_lshlrev_b32_e32 v93, 16, v22
	v_lshlrev_b32_e32 v92, 16, v18
	v_add_f32_dpp v5, v5, v5 row_ror:4 row_mask:0xf bank_mask:0xf bound_ctrl:1
	v_lshlrev_b32_e32 v96, 16, v19
	v_lshlrev_b32_e32 v97, 16, v23
	v_add_f32_dpp v5, v5, v5 quad_perm:[2,3,0,1] row_mask:0xf bank_mask:0xf bound_ctrl:1
	v_and_b32_e32 v23, 0xffff0000, v23
	s_nop 0
	v_add_f32_dpp v5, v5, v5 quad_perm:[1,0,3,2] row_mask:0xf bank_mask:0xf bound_ctrl:1
	v_fmamk_f32 v5, v5, 0x3c000000, v1
	v_rsq_f32_e32 v32, v5
	v_add_f32_e32 v5, v29, v33
	v_add_f32_e32 v5, v28, v5
	v_add_f32_e32 v5, v73, v5
	v_add_f32_e32 v5, v72, v5
	v_pk_mul_f32 v[28:29], v[90:91], v[64:65]
	v_lshlrev_b32_e32 v91, 16, v25
	v_add_f32_dpp v5, v5, v5 row_ror:8 row_mask:0xf bank_mask:0xf bound_ctrl:1
	v_lshlrev_b32_e32 v90, 16, v21
	v_mov_b32_e32 v107, v90
	v_add_f32_dpp v5, v5, v5 row_ror:4 row_mask:0xf bank_mask:0xf bound_ctrl:1
	v_pk_fma_f32 v[28:29], v[66:67], v[28:29], v[68:69] op_sel_hi:[0,1,0]
	s_nop 0
	v_add_f32_dpp v5, v5, v5 quad_perm:[2,3,0,1] row_mask:0xf bank_mask:0xf bound_ctrl:1
	s_nop 1
	v_add_f32_dpp v5, v5, v5 quad_perm:[1,0,3,2] row_mask:0xf bank_mask:0xf bound_ctrl:1
	v_fmamk_f32 v5, v5, 0x3c000000, v1
	v_rsq_f32_e32 v33, v5
	s_nop 0
	v_pk_mul_f32 v[64:65], v[84:85], v[32:33]
	v_mov_b32_e32 v84, v95
	v_mov_b32_e32 v95, v26
	v_pk_mul_f32 v[82:83], v[88:89], v[32:33]
	v_mov_b32_e32 v85, v27
	v_pk_mul_f32 v[26:27], v[94:95], v[32:33]
	v_and_b32_e32 v88, 0xffff0000, v21
	v_and_b32_e32 v89, 0xffff0000, v25
	v_and_b32_e32 v95, 0xffff0000, v22
	v_and_b32_e32 v94, 0xffff0000, v18
	v_and_b32_e32 v22, 0xffff0000, v19
	v_lshlrev_b32_e32 v19, 16, v24
	v_and_b32_e32 v21, 0xffff0000, v24
	v_pk_add_f32 v[24:25], v[92:93], 0 op_sel_hi:[1,0]
	v_lshlrev_b32_e32 v18, 16, v20
	v_pk_add_f32 v[24:25], v[24:25], v[94:95]
	v_and_b32_e32 v20, 0xffff0000, v20
	v_pk_add_f32 v[24:25], v[24:25], v[96:97]
	v_mov_b32_e32 v102, v20
	v_pk_add_f32 v[24:25], v[24:25], v[22:23]
	v_mov_b32_e32 v103, v18
	v_pk_add_f32 v[24:25], v[24:25], v[18:19]
	v_mov_b32_e32 v106, v88
	v_pk_add_f32 v[24:25], v[24:25], v[20:21]
	v_mov_b32_e32 v18, v21
	v_pk_add_f32 v[24:25], v[24:25], v[90:91]
	v_mov_b32_e32 v90, v89
	v_pk_add_f32 v[24:25], v[24:25], v[88:89]
	v_pk_mul_f32 v[72:73], v[86:87], v[32:33]
	v_mov_b32_e32 v86, v99
	v_mov_b32_dpp v100, v24 row_ror:8 row_mask:0xf bank_mask:0xf bound_ctrl:1
	v_mov_b32_dpp v101, v25 row_ror:8 row_mask:0xf bank_mask:0xf bound_ctrl:1
	v_pk_add_f32 v[24:25], v[24:25], v[100:101]
	v_mov_b32_e32 v87, v71
	v_pk_mul_f32 v[86:87], v[86:87], v[32:33]
	v_mov_b32_dpp v100, v24 row_ror:4 row_mask:0xf bank_mask:0xf bound_ctrl:1
	v_mov_b32_dpp v101, v25 row_ror:4 row_mask:0xf bank_mask:0xf bound_ctrl:1
	v_pk_add_f32 v[24:25], v[24:25], v[100:101]
	v_pk_fma_f32 v[86:87], v[4:5], v[86:87], v[8:9] op_sel_hi:[0,1,0]
	v_mov_b32_e32 v99, v70
	v_mov_b32_dpp v100, v24 quad_perm:[2,3,0,1] row_mask:0xf bank_mask:0xf bound_ctrl:1
	v_mov_b32_dpp v101, v25 quad_perm:[2,3,0,1] row_mask:0xf bank_mask:0xf bound_ctrl:1
	v_pk_add_f32 v[24:25], v[24:25], v[100:101]
	v_pk_mul_f32 v[30:31], v[30:31], v[32:33]
	v_pk_mul_f32 v[84:85], v[84:85], v[32:33]
	v_mov_b32_dpp v100, v24 quad_perm:[1,0,3,2] row_mask:0xf bank_mask:0xf bound_ctrl:1
; #define LAS __attribute__((address_space(3)))
; __device__ __forceinline__ unsigned pk2(float lo, float hi) { f32x2 v = {lo, hi}; bf16x2_t b = __builtin_convertvector(v, bf16x2_t); return __builtin_bit_cast(unsigned, b); }
; __device__ __forceinline__ void gmlp_unit(const GmlpP& P, int b, int ch, LAS unsigned char* lds, int wave, int lane_in) {
;     ...
;                 sm = row16_sum(sm);
;                 const float mu = sm * (1.0f / 128.0f);
;                 float sq = 0.f;
; #pragma unroll
;                 for (int j = 0; j < 8; ++j) { v[j] -= mu; sq += v[j] * v[j]; }
;                 sq = row16_sum(sq);
;                 const float rs = __builtin_amdgcn_rsqf(sq * (1.0f / 128.0f) + EPS);
; #pragma unroll
;                 for (int j = 0; j < 8; ++j) yv[j][i] = v[j] * rs * (j < 4 ? ga0[j & 3] : ga1[j & 3]) + (j < 4 ? be0[j & 3] : be1[j & 3]);
;             }
;             const int s0 = 64 * th + 16 * rr + 8 * hf;
;             LAS unsigned char* dst = lds + (gI * 128 + 8 * sub) * LDS_TT_PITCH + 16 * ((s0 >> 3) ^ sub);
; #pragma unroll
;             for (int j = 0; j < 8; ++j) {
;                 u32x4 w; w.x = pk2(yv[j][0], yv[j][1]); w.y = pk2(yv[j][2], yv[j][3]); w.z = pk2(yv[j][4], yv[j][5]); w.w = pk2(yv[j][6], yv[j][7]);
;                 *(LAS u32x4*)(dst + j * LDS_TT_PITCH) = w;
;             }
;             asm volatile("" ::: "memory");
;         }
;     }
;     const int r32 = lane & 31, h = lane >> 5;
;     const int tt0 = th, tt1 = 3 - th;
;     bf16x8 bw0[4], bw1[8];
;     { const bf16_t* w0p = P.wsb + ((size_t)(gI * 128 + 32 * tt0 + r32) * 128 + 8 * h);
;       const bf16_t* w1p = P.wsb + ((size_t)(gI * 128 + 32 * tt1 + r32) * 128 + 8 * h);
; #pragma unroll
;       for (int ks = 0; ks < 4; ++ks) bw0[ks] = *(const bf16x8*)(w0p + 16 * ks);
; #pragma unroll
;       for (int ks = 0; ks < 8; ++ks) bw1[ks] = *(const bf16x8*)(w1p + 16 * ks); }
;     __syncthreads();
	v_mov_b32_dpp v101, v25 quad_perm:[1,0,3,2] row_mask:0xf bank_mask:0xf bound_ctrl:1
	v_pk_add_f32 v[24:25], v[24:25], v[100:101]
	v_pk_fma_f32 v[64:65], v[10:11], v[64:65], v[14:15] op_sel_hi:[0,1,0]
	v_pk_mul_f32 v[100:101], v[24:25], s[24:25] op_sel_hi:[1,0]
	v_pk_fma_f32 v[94:95], v[24:25], s[24:25], v[94:95] op_sel_hi:[1,0,1] neg_lo:[1,0,0] neg_hi:[1,0,0]
	v_pk_fma_f32 v[92:93], v[24:25], s[24:25], v[92:93] op_sel_hi:[1,0,1] neg_lo:[1,0,0] neg_hi:[1,0,0]
	v_pk_add_f32 v[102:103], v[102:103], v[100:101] op_sel_hi:[1,0] neg_lo:[0,1] neg_hi:[0,1]
	v_pk_add_f32 v[106:107], v[106:107], v[100:101] op_sel_hi:[1,0] neg_lo:[0,1] neg_hi:[0,1]
	v_pk_add_f32 v[18:19], v[18:19], v[100:101] op_sel:[0,1] neg_lo:[0,1] neg_hi:[0,1]
	v_pk_add_f32 v[88:89], v[90:91], v[100:101] op_sel:[0,1] neg_lo:[0,1] neg_hi:[0,1]
	v_pk_mul_f32 v[100:101], v[94:95], v[94:95]
	v_pk_fma_f32 v[96:97], v[24:25], s[24:25], v[96:97] op_sel_hi:[1,0,1] neg_lo:[1,0,0] neg_hi:[1,0,0]
	v_pk_fma_f32 v[100:101], v[92:93], v[92:93], v[100:101]
	v_pk_fma_f32 v[22:23], v[24:25], s[24:25], v[22:23] op_sel_hi:[1,0,1] neg_lo:[1,0,0] neg_hi:[1,0,0]
	v_pk_fma_f32 v[100:101], v[96:97], v[96:97], v[100:101]
	v_pk_mul_f32 v[104:105], v[102:103], v[102:103]
	v_pk_fma_f32 v[24:25], v[22:23], v[22:23], v[100:101]
	v_pk_mul_f32 v[110:111], v[106:107], v[106:107]
	v_add_f32_e32 v5, v105, v24
	v_add_f32_e32 v5, v104, v5
	v_add_f32_e32 v5, v111, v5
	v_add_f32_e32 v5, v110, v5
	v_pk_mul_f32 v[20:21], v[18:19], v[18:19]
	v_pk_mul_f32 v[90:91], v[88:89], v[88:89]
	v_add_f32_dpp v5, v5, v5 row_ror:8 row_mask:0xf bank_mask:0xf bound_ctrl:1
	v_pk_fma_f32 v[72:73], v[10:11], v[72:73], v[14:15] op_sel:[1,0,1]
	v_pk_fma_f32 v[82:83], v[12:13], v[82:83], v[16:17] op_sel_hi:[0,1,0]
	v_add_f32_dpp v5, v5, v5 row_ror:4 row_mask:0xf bank_mask:0xf bound_ctrl:1
	v_pk_fma_f32 v[84:85], v[2:3], v[84:85], v[6:7] op_sel_hi:[0,1,0]
	v_pk_fma_f32 v[30:31], v[74:75], v[30:31], v[76:77] op_sel_hi:[0,1,0]
	v_add_f32_dpp v5, v5, v5 quad_perm:[2,3,0,1] row_mask:0xf bank_mask:0xf bound_ctrl:1
	v_pk_fma_f32 v[26:27], v[78:79], v[26:27], v[80:81] op_sel_hi:[0,1,0]
	s_nop 0
	v_add_f32_dpp v5, v5, v5 quad_perm:[1,0,3,2] row_mask:0xf bank_mask:0xf bound_ctrl:1
	v_fmamk_f32 v5, v5, 0x3c000000, v1
	v_rsq_f32_e32 v24, v5
	v_add_f32_e32 v5, v21, v25
	v_add_f32_e32 v5, v20, v5
	v_add_f32_e32 v5, v91, v5
	v_add_f32_e32 v5, v90, v5
	v_pk_mul_f32 v[20:21], v[98:99], v[32:33]
	s_nop 0
	v_add_f32_dpp v5, v5, v5 row_ror:8 row_mask:0xf bank_mask:0xf bound_ctrl:1
	v_pk_fma_f32 v[20:21], v[66:67], v[20:21], v[68:69] op_sel_hi:[0,1,0]
	s_nop 0
	v_add_f32_dpp v5, v5, v5 row_ror:4 row_mask:0xf bank_mask:0xf bound_ctrl:1
	s_nop 1
	v_add_f32_dpp v5, v5, v5 quad_perm:[2,3,0,1] row_mask:0xf bank_mask:0xf bound_ctrl:1
	s_nop 1
	v_add_f32_dpp v5, v5, v5 quad_perm:[1,0,3,2] row_mask:0xf bank_mask:0xf bound_ctrl:1
	v_fmamk_f32 v5, v5, 0x3c000000, v1
	v_rsq_f32_e32 v25, v5
	s_nop 0
	v_pk_mul_f32 v[32:33], v[92:93], v[24:25]
	v_pk_mul_f32 v[70:71], v[94:95], v[24:25]
	v_pk_fma_f32 v[32:33], v[10:11], v[32:33], v[14:15] op_sel_hi:[0,1,0]
	v_pk_fma_f32 v[10:11], v[10:11], v[70:71], v[14:15] op_sel:[1,0,1]
	v_pk_mul_f32 v[14:15], v[96:97], v[24:25]
	s_nop 0
	v_pk_fma_f32 v[12:13], v[12:13], v[14:15], v[16:17] op_sel_hi:[0,1,0]
	v_mov_b32_e32 v16, v103
	v_mov_b32_e32 v17, v19
	v_mov_b32_e32 v103, v18
	v_mov_b32_e32 v18, v107
	v_mov_b32_e32 v19, v89
	v_pk_mul_f32 v[16:17], v[16:17], v[24:25]
	v_pk_mul_f32 v[18:19], v[18:19], v[24:25]
	v_mov_b32_e32 v107, v88
	v_pk_fma_f32 v[6:7], v[2:3], v[16:17], v[6:7] op_sel_hi:[0,1,0]
	v_pk_fma_f32 v[8:9], v[4:5], v[18:19], v[8:9] op_sel_hi:[0,1,0]
	v_pk_mul_f32 v[4:5], v[106:107], v[24:25]
	v_bitop3_b32 v2, v3, v108, 1 bitop3:0x36
	v_pk_mul_f32 v[14:15], v[22:23], v[24:25]
	v_pk_fma_f32 v[18:19], v[66:67], v[4:5], v[68:69] op_sel_hi:[0,1,0]
	v_lshl_add_u32 v22, v2, 4, v75
	v_cvt_pk_bf16_f32 v2, v54, v55
	v_cvt_pk_bf16_f32 v3, v62, v63
	v_cvt_pk_bf16_f32 v4, v64, v65
	v_cvt_pk_bf16_f32 v5, v32, v33
	ds_write_b128 v22, v[2:5]
	v_cvt_pk_bf16_f32 v2, v52, v53
	v_cvt_pk_bf16_f32 v3, v60, v61
	v_cvt_pk_bf16_f32 v4, v72, v73
	v_cvt_pk_bf16_f32 v5, v10, v11
	v_pk_fma_f32 v[14:15], v[74:75], v[14:15], v[76:77] op_sel_hi:[0,1,0]
	ds_write_b128 v22, v[2:5] offset:272
	v_cvt_pk_bf16_f32 v2, v50, v51
	v_cvt_pk_bf16_f32 v3, v58, v59
	v_cvt_pk_bf16_f32 v4, v82, v83
	v_cvt_pk_bf16_f32 v5, v12, v13
	v_pk_mul_f32 v[16:17], v[102:103], v[24:25]
	ds_write_b128 v22, v[2:5] offset:544
	v_cvt_pk_bf16_f32 v2, v48, v49
	v_cvt_pk_bf16_f32 v3, v56, v57
	v_cvt_pk_bf16_f32 v4, v30, v31
	v_cvt_pk_bf16_f32 v5, v14, v15
	v_pk_fma_f32 v[16:17], v[78:79], v[16:17], v[80:81] op_sel_hi:[0,1,0]
	ds_write_b128 v22, v[2:5] offset:816
	v_cvt_pk_bf16_f32 v2, v46, v47
	v_cvt_pk_bf16_f32 v3, v40, v41
	v_cvt_pk_bf16_f32 v4, v84, v85
	v_cvt_pk_bf16_f32 v5, v6, v7
	ds_write_b128 v22, v[2:5] offset:1088
	v_cvt_pk_bf16_f32 v2, v44, v45
	v_cvt_pk_bf16_f32 v3, v38, v39
	v_cvt_pk_bf16_f32 v4, v26, v27
	v_cvt_pk_bf16_f32 v5, v16, v17
	ds_write_b128 v22, v[2:5] offset:1360
	v_cvt_pk_bf16_f32 v2, v42, v43
	v_cvt_pk_bf16_f32 v3, v36, v37
	v_cvt_pk_bf16_f32 v4, v86, v87
	v_cvt_pk_bf16_f32 v5, v8, v9
	ds_write_b128 v22, v[2:5] offset:1632
	v_cvt_pk_bf16_f32 v2, v34, v35
	v_cvt_pk_bf16_f32 v3, v28, v29
	v_cvt_pk_bf16_f32 v4, v20, v21
	v_cvt_pk_bf16_f32 v5, v18, v19
	ds_write_b128 v22, v[2:5] offset:1904
	v_or_b32_e32 v2, s22, v154
	v_ashrrev_i32_e32 v3, 31, v2
	v_lshlrev_b32_e32 v4, 3, v140
	v_ashrrev_i32_e32 v5, 31, v4
	v_lshlrev_b64 v[2:3], 8, v[2:3]
	v_lshl_add_u64 v[2:3], s[0:1], 0, v[2:3]
	v_lshlrev_b64 v[6:7], 1, v[4:5]
	v_lshl_add_u64 v[10:11], v[2:3], 0, v[6:7]
	global_load_dwordx4 v[2:5], v[10:11], off
	v_or_b32_e32 v8, s25, v154
	v_ashrrev_i32_e32 v9, 31, v8
	v_lshlrev_b64 v[8:9], 8, v[8:9]
	v_lshl_add_u64 v[8:9], s[0:1], 0, v[8:9]
	v_lshl_add_u64 v[12:13], v[8:9], 0, v[6:7]
	global_load_dwordx4 v[6:9], v[12:13], off
	global_load_dwordx4 v[144:147], v[10:11], off offset:32
	global_load_dwordx4 v[148:151], v[10:11], off offset:64
	global_load_dwordx4 v[156:159], v[10:11], off offset:96
	global_load_dwordx4 v[160:163], v[12:13], off offset:32
	global_load_dwordx4 v[164:167], v[12:13], off offset:64
	global_load_dwordx4 v[168:171], v[12:13], off offset:96
	global_load_dwordx4 v[172:175], v[12:13], off offset:128
	global_load_dwordx4 v[176:179], v[12:13], off offset:160
	global_load_dwordx4 v[134:137], v[12:13], off offset:192
	global_load_dwordx4 v[130:133], v[12:13], off offset:224
	v_or_b32_e32 v14, 32, v154
	v_or_b32_e32 v10, s6, v154
	v_or_b32_e32 v15, s6, v14
	v_mul_lo_u32 v10, v10, s48
	v_mul_lo_u32 v15, v15, s48
	v_lshrrev_b32_e32 v190, 3, v14
	v_add_u32_e32 v155, 0, v10
	v_xor_b32_e32 v10, v188, v140
	v_add_u32_e32 v189, 0, v15
	v_xor_b32_e32 v14, v190, v140
	v_lshl_add_u32 v10, v10, 4, v155
	v_lshl_add_u32 v14, v14, 4, v189
	s_waitcnt lgkmcnt(0)
	s_barrier
; #define LAS __attribute__((address_space(3)))
; __device__ __forceinline__ void gmlp_unit(const GmlpP& P, int b, int ch, LAS unsigned char* lds, int wave, int lane_in) {
;     ...
;     {
; #pragma unroll
;         for (int ks = 0; ks < 8; ++ks)
; #pragma unroll
;             for (int mt = 0; mt < 4; ++mt) {
;                 const int cc = 32 * mt + r32;
;                 const bf16x8 a = *(const LAS bf16x8*)(lds + (gI * 128 + cc) * LDS_TT_PITCH + 16 * ((2 * ks + h) ^ ((cc >> 3) & 15)));
;                 if (ks < 4) acc[mt][0] = __builtin_amdgcn_mfma_f32_32x32x16_bf16(a, bw0[ks], acc[mt][0], 0, 0, 0);
;                 acc[mt][1] = __builtin_amdgcn_mfma_f32_32x32x16_bf16(a, bw1[ks], acc[mt][1], 0, 0, 0);
;                 if (mt == 3 && (ks & 1)) asm volatile("" ::: "memory");
;             }
;     }
	ds_read_b128 v[10:13], v10
	ds_read_b128 v[14:17], v14
	s_waitcnt vmcnt(11) lgkmcnt(1)
	v_mfma_f32_32x32x16_bf16 v[114:129], v[10:13], v[2:5], 0
	v_lshl_add_u32 v153, v153, 4, v155
	ds_read_b128 v[180:183], v153
	v_xor_b32_e32 v153, v190, v152
	v_lshl_add_u32 v153, v153, 4, v189
	ds_read_b128 v[184:187], v153
	s_waitcnt vmcnt(10)
	v_mfma_f32_32x32x16_bf16 v[50:65], v[10:13], v[6:9], 0
	v_or_b32_e32 v10, 64, v154
	v_or_b32_e32 v11, s6, v10
	v_mul_lo_u32 v11, v11, s48
	v_lshrrev_b32_e32 v192, 3, v10
	v_add_u32_e32 v191, 0, v11
	v_xor_b32_e32 v10, v192, v140
	v_lshl_add_u32 v10, v10, 4, v191
	s_waitcnt lgkmcnt(2)
	v_mfma_f32_32x32x16_bf16 v[98:113], v[14:17], v[2:5], 0
	ds_read_b128 v[10:13], v10
	v_xor_b32_e32 v153, v192, v152
	v_lshl_add_u32 v153, v153, 4, v191
	v_mfma_f32_32x32x16_bf16 v[34:49], v[14:17], v[6:9], 0
	v_or_b32_e32 v14, 0x60, v154
	v_or_b32_e32 v15, s6, v14
	v_mul_lo_u32 v15, v15, s48
	v_lshrrev_b32_e32 v194, 3, v14
	v_add_u32_e32 v193, 0, v15
	v_xor_b32_e32 v14, v194, v140
	v_lshl_add_u32 v14, v14, 4, v193
	ds_read_b128 v[14:17], v14
	v_xor_b32_e32 v152, v194, v152
	v_lshl_add_u32 v152, v152, 4, v193
	s_waitcnt vmcnt(9) lgkmcnt(3)
	v_mfma_f32_32x32x16_bf16 v[114:129], v[180:183], v[144:147], v[114:129]
	s_waitcnt vmcnt(6)
	v_mfma_f32_32x32x16_bf16 v[50:65], v[180:183], v[160:163], v[50:65]
	ds_read_b128 v[180:183], v153
	s_waitcnt lgkmcnt(3)
	v_mfma_f32_32x32x16_bf16 v[98:113], v[184:187], v[144:147], v[98:113]
	v_mfma_f32_32x32x16_bf16 v[34:49], v[184:187], v[160:163], v[34:49]
	ds_read_b128 v[184:187], v152
	v_add_u32_e32 v152, 4, v140
	v_xor_b32_e32 v153, v190, v152
	v_lshl_add_u32 v153, v153, 4, v189
	s_waitcnt lgkmcnt(3)
	v_mfma_f32_32x32x16_bf16 v[82:97], v[10:13], v[2:5], 0
	s_waitcnt lgkmcnt(2)
	v_mfma_f32_32x32x16_bf16 v[66:81], v[14:17], v[2:5], 0
	s_waitcnt lgkmcnt(1)
	v_mfma_f32_32x32x16_bf16 v[82:97], v[180:183], v[144:147], v[82:97]
	s_waitcnt lgkmcnt(0)
	v_mfma_f32_32x32x16_bf16 v[66:81], v[184:187], v[144:147], v[66:81]
	v_xor_b32_e32 v144, v188, v152
	v_lshl_add_u32 v144, v144, 4, v155
	ds_read_b128 v[144:147], v144
	v_mfma_f32_32x32x16_bf16 v[18:33], v[10:13], v[6:9], 0
	v_mfma_f32_32x32x16_bf16 v[2:17], v[14:17], v[6:9], 0
	v_mfma_f32_32x32x16_bf16 v[18:33], v[180:183], v[160:163], v[18:33]
	v_mfma_f32_32x32x16_bf16 v[2:17], v[184:187], v[160:163], v[2:17]
	ds_read_b128 v[160:163], v153
	s_waitcnt lgkmcnt(1)
	v_mfma_f32_32x32x16_bf16 v[114:129], v[144:147], v[148:151], v[114:129]
	s_waitcnt vmcnt(5)
	v_mfma_f32_32x32x16_bf16 v[50:65], v[144:147], v[164:167], v[50:65]
	v_xor_b32_e32 v144, v192, v152
	v_lshl_add_u32 v144, v144, 4, v191
	ds_read_b128 v[144:147], v144
	v_xor_b32_e32 v152, v194, v152
	v_lshl_add_u32 v152, v152, 4, v193
	s_waitcnt lgkmcnt(1)
	v_mfma_f32_32x32x16_bf16 v[98:113], v[160:163], v[148:151], v[98:113]
	v_mfma_f32_32x32x16_bf16 v[34:49], v[160:163], v[164:167], v[34:49]
	ds_read_b128 v[160:163], v152
	v_add_u32_e32 v152, 6, v140
	s_waitcnt lgkmcnt(1)
	v_mfma_f32_32x32x16_bf16 v[82:97], v[144:147], v[148:151], v[82:97]
	v_mfma_f32_32x32x16_bf16 v[18:33], v[144:147], v[164:167], v[18:33]
	v_xor_b32_e32 v144, v188, v152
	v_lshl_add_u32 v144, v144, 4, v155
	ds_read_b128 v[144:147], v144
	s_waitcnt lgkmcnt(1)
	v_mfma_f32_32x32x16_bf16 v[66:81], v[160:163], v[148:151], v[66:81]
	v_xor_b32_e32 v148, v190, v152
	v_lshl_add_u32 v148, v148, 4, v189
	ds_read_b128 v[148:151], v148
	s_waitcnt lgkmcnt(1)
	v_mfma_f32_32x32x16_bf16 v[114:129], v[144:147], v[156:159], v[114:129]
	s_waitcnt vmcnt(4)
	v_mfma_f32_32x32x16_bf16 v[50:65], v[144:147], v[168:171], v[50:65]
	v_xor_b32_e32 v144, v192, v152
	v_lshl_add_u32 v144, v144, 4, v191
	ds_read_b128 v[144:147], v144
	s_waitcnt lgkmcnt(1)
	v_mfma_f32_32x32x16_bf16 v[98:113], v[148:151], v[156:159], v[98:113]
	v_mfma_f32_32x32x16_bf16 v[34:49], v[148:151], v[168:171], v[34:49]
	v_xor_b32_e32 v148, v194, v152
	v_lshl_add_u32 v148, v148, 4, v193
	v_add_u32_e32 v152, 8, v140
	ds_read_b128 v[148:151], v148
	s_waitcnt lgkmcnt(1)
	v_mfma_f32_32x32x16_bf16 v[82:97], v[144:147], v[156:159], v[82:97]
	v_mfma_f32_32x32x16_bf16 v[18:33], v[144:147], v[168:171], v[18:33]
	v_xor_b32_e32 v144, v188, v152
	v_lshl_add_u32 v144, v144, 4, v155
	ds_read_b128 v[144:147], v144
	v_mfma_f32_32x32x16_bf16 v[2:17], v[160:163], v[164:167], v[2:17]
	s_waitcnt lgkmcnt(1)
	v_mfma_f32_32x32x16_bf16 v[66:81], v[148:151], v[156:159], v[66:81]
	v_or_b32_e32 v157, s21, v154
	v_or_b32_e32 v156, s50, v157
	v_mfma_f32_32x32x16_bf16 v[2:17], v[148:151], v[168:171], v[2:17]
	v_xor_b32_e32 v148, v190, v152
	v_lshl_add_u32 v148, v148, 4, v189
	ds_read_b128 v[148:151], v148
	s_waitcnt vmcnt(3) lgkmcnt(1)
	v_mfma_f32_32x32x16_bf16 v[50:65], v[144:147], v[172:175], v[50:65]
	v_xor_b32_e32 v144, v192, v152
	v_lshl_add_u32 v144, v144, 4, v191
	ds_read_b128 v[144:147], v144
	s_waitcnt lgkmcnt(1)
	v_mfma_f32_32x32x16_bf16 v[34:49], v[148:151], v[172:175], v[34:49]
	v_xor_b32_e32 v148, v194, v152
	v_lshl_add_u32 v148, v148, 4, v193
	v_add_u32_e32 v152, 10, v140
	ds_read_b128 v[148:151], v148
	s_waitcnt lgkmcnt(1)
	v_mfma_f32_32x32x16_bf16 v[18:33], v[144:147], v[172:175], v[18:33]
	v_xor_b32_e32 v144, v188, v152
	v_lshl_add_u32 v144, v144, 4, v155
	ds_read_b128 v[144:147], v144
	s_waitcnt lgkmcnt(1)
	v_mfma_f32_32x32x16_bf16 v[2:17], v[148:151], v[172:175], v[2:17]
	v_xor_b32_e32 v148, v190, v152
	v_lshl_add_u32 v148, v148, 4, v189
	ds_read_b128 v[148:151], v148
	s_waitcnt vmcnt(2) lgkmcnt(1)
	v_mfma_f32_32x32x16_bf16 v[50:65], v[144:147], v[176:179], v[50:65]
	v_xor_b32_e32 v144, v192, v152
	v_lshl_add_u32 v144, v144, 4, v191
	ds_read_b128 v[144:147], v144
	s_waitcnt lgkmcnt(1)
; #define LAS __attribute__((address_space(3)))
; __device__ __forceinline__ void gmlp_unit(const GmlpP& P, int b, int ch, LAS unsigned char* lds, int wave, int lane_in) {
;     ...
;         for (int ks = 0; ks < 8; ++ks)
; #pragma unroll
;             for (int mt = 0; mt < 4; ++mt) {
;                 const int cc = 32 * mt + r32;
;                 const bf16x8 a = *(const LAS bf16x8*)(lds + (gI * 128 + cc) * LDS_TT_PITCH + 16 * ((2 * ks + h) ^ ((cc >> 3) & 15)));
;                 if (ks < 4) acc[mt][0] = __builtin_amdgcn_mfma_f32_32x32x16_bf16(a, bw0[ks], acc[mt][0], 0, 0, 0);
;                 acc[mt][1] = __builtin_amdgcn_mfma_f32_32x32x16_bf16(a, bw1[ks], acc[mt][1], 0, 0, 0);
;                 if (mt == 3 && (ks & 1)) asm volatile("" ::: "memory");
;             }
;     }
;     LAS float* ssqg = (LAS float*)(lds + LDS_SSQG);
; #pragma unroll
;     for (int nt = 0; nt < 2; ++nt) {
;         const int t = 32 * (nt == 0 ? tt0 : tt1) + r32;
;         const float bsv = P.bs[gI * 128 + t];
;         const bf16_t* up = P.U + (tok0 + t) * GW + gI * 128 + 4 * h;
;         float ss = 0.f;
;         u32x2 uraw[4][4];
; #pragma unroll
;         for (int mt = 0; mt < 4; ++mt)
; #pragma unroll
;             for (int e4 = 0; e4 < 4; ++e4) uraw[mt][e4] = *(const u32x2*)(up + 32 * mt + 8 * e4);
	v_mfma_f32_32x32x16_bf16 v[34:49], v[148:151], v[176:179], v[34:49]
	v_xor_b32_e32 v148, v194, v152
	v_lshl_add_u32 v148, v148, 4, v193
	v_add_u32_e32 v152, 12, v140
	ds_read_b128 v[148:151], v148
	s_waitcnt lgkmcnt(1)
	v_mfma_f32_32x32x16_bf16 v[18:33], v[144:147], v[176:179], v[18:33]
	v_xor_b32_e32 v144, v188, v152
	v_lshl_add_u32 v144, v144, 4, v155
	ds_read_b128 v[144:147], v144
	s_waitcnt lgkmcnt(1)
	v_mfma_f32_32x32x16_bf16 v[2:17], v[148:151], v[176:179], v[2:17]
	v_xor_b32_e32 v148, v190, v152
	v_lshl_add_u32 v148, v148, 4, v189
	ds_read_b128 v[148:151], v148
	s_waitcnt vmcnt(1) lgkmcnt(1)
	v_mfma_f32_32x32x16_bf16 v[50:65], v[144:147], v[134:137], v[50:65]
	v_xor_b32_e32 v144, v192, v152
	v_lshl_add_u32 v144, v144, 4, v191
	ds_read_b128 v[144:147], v144
	s_waitcnt lgkmcnt(1)
	v_mfma_f32_32x32x16_bf16 v[34:49], v[148:151], v[134:137], v[34:49]
	v_xor_b32_e32 v148, v194, v152
	v_lshl_add_u32 v148, v148, 4, v193
	ds_read_b128 v[150:153], v148
	v_or_b32_e32 v148, s6, v157
	v_ashrrev_i32_e32 v149, 31, v148
	v_lshl_add_u64 v[178:179], v[148:149], 2, s[40:41]
	s_waitcnt lgkmcnt(1)
	v_mfma_f32_32x32x16_bf16 v[18:33], v[144:147], v[134:137], v[18:33]
	v_add_u32_e32 v144, 14, v140
	v_xor_b32_e32 v145, v188, v144
	v_lshl_add_u32 v145, v145, 4, v155
	v_xor_b32_e32 v146, v190, v144
	v_lshl_add_u32 v146, v146, 4, v189
	ds_read_b128 v[158:161], v145
	ds_read_b128 v[162:165], v146
	v_xor_b32_e32 v145, v192, v144
	v_xor_b32_e32 v144, v194, v144
	v_lshl_add_u32 v145, v145, 4, v191
	v_lshl_add_u32 v144, v144, 4, v193
	ds_read_b128 v[166:169], v145
	ds_read_b128 v[170:173], v144
	v_lshlrev_b32_e32 v144, 2, v140
	v_ashrrev_i32_e32 v145, 31, v144
	v_lshl_add_u64 v[146:147], v[144:145], 1, s[14:15]
	v_lshlrev_b32_e32 v140, 10, v156
	v_lshl_add_u64 v[174:175], v[146:147], 0, v[140:141]
	global_load_dword v140, v[178:179], off
	v_bfe_u32 v234, v0, 5, 1
	v_lshlrev_b32_e32 v234, 3, v234
	v_mov_b32_e32 v235, 0
	v_lshl_add_u64 v[234:235], v[174:175], 0, v[234:235]
	v_and_b32_e32 v237, 63, v0
	v_lshrrev_b32_e32 v240, 1, v237
	v_and_b32_e32 v241, 1, v237
	v_and_b32_e32 v238, 31, v237
	v_lshrrev_b32_e32 v239, 5, v237
	v_lshl_add_u32 v236, v238, 1, v239
	v_lshlrev_b32_e32 v236, 2, v236
	v_sub_u32_e32 v238, v240, v238
	v_sub_u32_e32 v239, v241, v239
	v_lshlrev_b32_e32 v238, 10, v238
	v_lshl_add_u32 v238, v239, 4, v238
	v_ashrrev_i32_e32 v239, 31, v238
	v_lshl_add_u64 v[234:235], v[234:235], 0, v[238:239]
	global_load_dwordx4 v[202:205], v[234:235], off
	global_load_dwordx4 v[206:209], v[234:235], off offset:32
	global_load_dwordx4 v[210:213], v[234:235], off offset:64
	global_load_dwordx4 v[214:217], v[234:235], off offset:96
	global_load_dwordx4 v[218:221], v[234:235], off offset:128
	global_load_dwordx4 v[222:225], v[234:235], off offset:160
	global_load_dwordx4 v[226:229], v[234:235], off offset:192
	global_load_dwordx4 v[230:233], v[234:235], off offset:224
	s_waitcnt vmcnt(9) lgkmcnt(3)
	v_mfma_f32_32x32x16_bf16 v[50:65], v[158:161], v[130:133], v[50:65]
	s_waitcnt vmcnt(8)
	v_add_f32_e64 v114, v114, v140
	v_add_f32_e64 v115, v115, v140
	s_waitcnt lgkmcnt(2)
	v_mfma_f32_32x32x16_bf16 v[34:49], v[162:165], v[130:133], v[34:49]
	v_add_f32_e64 v116, v116, v140
	v_add_f32_e64 v117, v117, v140
	v_add_f32_e64 v118, v118, v140
	v_add_f32_e64 v119, v119, v140
	v_pk_add_f32 v[120:121], v[120:121], v[140:141] op_sel_hi:[1,0]
	v_pk_add_f32 v[122:123], v[122:123], v[140:141] op_sel_hi:[1,0]
	v_pk_add_f32 v[124:125], v[124:125], v[140:141] op_sel_hi:[1,0]
	v_pk_add_f32 v[126:127], v[126:127], v[140:141] op_sel_hi:[1,0]
	v_mfma_f32_32x32x16_bf16 v[2:17], v[150:153], v[134:137], v[2:17]
	v_add_f32_e64 v128, v128, v140
	v_add_f32_e64 v129, v129, v140
	v_add_f32_e64 v98, v98, v140
	v_add_f32_e64 v99, v99, v140
	v_add_f32_e64 v100, v100, v140
	v_add_f32_e64 v101, v101, v140
	v_pk_add_f32 v[102:103], v[102:103], v[140:141] op_sel_hi:[1,0]
	v_pk_add_f32 v[104:105], v[104:105], v[140:141] op_sel_hi:[1,0]
	v_pk_add_f32 v[106:107], v[106:107], v[140:141] op_sel_hi:[1,0]
	v_pk_add_f32 v[108:109], v[108:109], v[140:141] op_sel_hi:[1,0]
	s_waitcnt lgkmcnt(1)
	v_mfma_f32_32x32x16_bf16 v[18:33], v[166:169], v[130:133], v[18:33]
	v_add_f32_e64 v110, v110, v140
	v_add_f32_e64 v111, v111, v140
	v_add_f32_e64 v112, v112, v140
	v_add_f32_e64 v113, v113, v140
	v_add_f32_e64 v82, v82, v140
	v_add_f32_e64 v83, v83, v140
	v_pk_add_f32 v[84:85], v[84:85], v[140:141] op_sel_hi:[1,0]
	v_pk_add_f32 v[86:87], v[86:87], v[140:141] op_sel_hi:[1,0]
	v_pk_add_f32 v[88:89], v[88:89], v[140:141] op_sel_hi:[1,0]
	v_pk_add_f32 v[90:91], v[90:91], v[140:141] op_sel_hi:[1,0]
	s_waitcnt lgkmcnt(0)
	v_mfma_f32_32x32x16_bf16 v[2:17], v[170:173], v[130:133], v[2:17]
	s_waitcnt vmcnt(0)
	ds_bpermute_b32 v202, v236, v202
	ds_bpermute_b32 v203, v236, v203
	ds_bpermute_b32 v204, v236, v204
	ds_bpermute_b32 v205, v236, v205
	ds_bpermute_b32 v206, v236, v206
	ds_bpermute_b32 v207, v236, v207
	ds_bpermute_b32 v208, v236, v208
	ds_bpermute_b32 v209, v236, v209
	ds_bpermute_b32 v210, v236, v210
	ds_bpermute_b32 v211, v236, v211
	ds_bpermute_b32 v212, v236, v212
	ds_bpermute_b32 v213, v236, v213
	ds_bpermute_b32 v214, v236, v214
	ds_bpermute_b32 v215, v236, v215
	ds_bpermute_b32 v216, v236, v216
	ds_bpermute_b32 v217, v236, v217
	ds_bpermute_b32 v218, v236, v218
	ds_bpermute_b32 v219, v236, v219
	ds_bpermute_b32 v220, v236, v220
	ds_bpermute_b32 v221, v236, v221
	ds_bpermute_b32 v222, v236, v222
	ds_bpermute_b32 v223, v236, v223
	ds_bpermute_b32 v224, v236, v224
	ds_bpermute_b32 v225, v236, v225
	ds_bpermute_b32 v226, v236, v226
	ds_bpermute_b32 v227, v236, v227
	ds_bpermute_b32 v228, v236, v228
	ds_bpermute_b32 v229, v236, v229
	ds_bpermute_b32 v230, v236, v230
	ds_bpermute_b32 v231, v236, v231
	ds_bpermute_b32 v232, v236, v232
	ds_bpermute_b32 v233, v236, v233
	s_waitcnt lgkmcnt(0)
; __device__ __forceinline__ void gmlp_unit(const GmlpP& P, int b, int ch, LAS unsigned char* lds, int wave, int lane_in) {
;     ...
; #pragma unroll
;         for (int mt = 0; mt < 4; ++mt)
; #pragma unroll
;             for (int e4 = 0; e4 < 4; ++e4) {
;                 const u32x2 raw = uraw[mt][e4];
;                 const float u0 = __builtin_bit_cast(float, raw.x << 16), u1 = __builtin_bit_cast(float, raw.x & 0xffff0000u);
;                 const float u2 = __builtin_bit_cast(float, raw.y << 16), u3 = __builtin_bit_cast(float, raw.y & 0xffff0000u);
;                 float m0 = u0 * (acc[mt][nt][4 * e4] + bsv), m1 = u1 * (acc[mt][nt][4 * e4 + 1] + bsv), m2 = u2 * (acc[mt][nt][4 * e4 + 2] + bsv), m3 = u3 * (acc[mt][nt][4 * e4 + 3] + bsv);
;                 acc[mt][nt][4 * e4] = m0; acc[mt][nt][4 * e4 + 1] = m1; acc[mt][nt][4 * e4 + 2] = m2; acc[mt][nt][4 * e4 + 3] = m3;
;                 ss += (m0 * m0 + m1 * m1) + (m2 * m2 + m3 * m3);
;             }
	v_permlane32_swap_b32_e32 v202, v204
	v_permlane32_swap_b32_e32 v203, v205
	v_permlane32_swap_b32_e32 v206, v208
	v_permlane32_swap_b32_e32 v207, v209
	v_permlane32_swap_b32_e32 v210, v212
	v_permlane32_swap_b32_e32 v211, v213
	v_permlane32_swap_b32_e32 v214, v216
	v_permlane32_swap_b32_e32 v215, v217
	v_permlane32_swap_b32_e32 v218, v220
	v_permlane32_swap_b32_e32 v219, v221
	v_permlane32_swap_b32_e32 v222, v224
	v_permlane32_swap_b32_e32 v223, v225
	v_permlane32_swap_b32_e32 v226, v228
	v_permlane32_swap_b32_e32 v227, v229
	v_permlane32_swap_b32_e32 v230, v232
	v_permlane32_swap_b32_e32 v231, v233
	v_mov_b32_e32 v176, v202
	v_mov_b32_e32 v177, v203
	v_mov_b32_e32 v178, v204
	v_mov_b32_e32 v179, v205
	v_mov_b32_e32 v158, v206
	v_mov_b32_e32 v159, v207
	v_mov_b32_e32 v160, v208
	v_mov_b32_e32 v161, v209
	v_mov_b32_e32 v162, v210
	v_mov_b32_e32 v163, v211
	v_mov_b32_e32 v164, v212
	v_mov_b32_e32 v165, v213
	v_mov_b32_e32 v166, v214
	v_mov_b32_e32 v167, v215
	v_mov_b32_e32 v168, v216
	v_mov_b32_e32 v169, v217
	v_mov_b32_e32 v170, v218
	v_mov_b32_e32 v171, v219
	v_mov_b32_e32 v172, v220
	v_mov_b32_e32 v173, v221
	v_mov_b32_e32 v180, v222
	v_mov_b32_e32 v181, v223
	v_mov_b32_e32 v152, v224
	v_mov_b32_e32 v153, v225
	v_mov_b32_e32 v150, v226
	v_mov_b32_e32 v151, v227
	v_mov_b32_e32 v136, v228
	v_mov_b32_e32 v137, v229
	v_mov_b32_e32 v134, v230
	v_mov_b32_e32 v135, v231
	v_mov_b32_e32 v132, v232
	v_mov_b32_e32 v133, v233
	v_lshlrev_b32_e32 v130, 16, v176
	v_and_b32_e32 v131, 0xffff0000, v176
	v_pk_mul_f32 v[114:115], v[114:115], v[130:131]
	v_lshlrev_b32_e32 v130, 16, v177
	v_and_b32_e32 v131, 0xffff0000, v177
	v_pk_mul_f32 v[116:117], v[116:117], v[130:131]
	v_mul_f32_e32 v130, v115, v115
	v_mul_f32_e32 v174, v117, v117
	v_pk_fma_f32 v[130:131], v[114:115], v[114:115], v[130:131] op_sel_hi:[1,1,0]
	v_pk_fma_f32 v[174:175], v[116:117], v[116:117], v[174:175] op_sel_hi:[1,1,0]
	v_pk_add_f32 v[92:93], v[92:93], v[140:141] op_sel_hi:[1,0]
	v_pk_add_f32 v[174:175], v[130:131], v[174:175]
	s_waitcnt vmcnt(14)
	v_lshlrev_b32_e32 v130, 16, v178
	v_and_b32_e32 v131, 0xffff0000, v178
	v_pk_mul_f32 v[118:119], v[118:119], v[130:131]
	v_lshlrev_b32_e32 v130, 16, v179
	v_and_b32_e32 v131, 0xffff0000, v179
	v_pk_mul_f32 v[130:131], v[120:121], v[130:131]
	v_mul_f32_e32 v120, v119, v119
	v_mul_f32_e32 v176, v131, v131
	v_pk_fma_f32 v[120:121], v[118:119], v[118:119], v[120:121] op_sel_hi:[1,1,0]
	v_pk_fma_f32 v[176:177], v[130:131], v[130:131], v[176:177] op_sel_hi:[1,1,0]
	v_pk_add_f32 v[94:95], v[94:95], v[140:141] op_sel_hi:[1,0]
	v_pk_add_f32 v[120:121], v[120:121], v[176:177]
	v_pk_add_f32 v[96:97], v[96:97], v[140:141] op_sel_hi:[1,0]
	v_pk_add_f32 v[174:175], v[174:175], v[120:121]
	s_waitcnt vmcnt(13)
	v_lshlrev_b32_e32 v120, 16, v158
	v_and_b32_e32 v121, 0xffff0000, v158
	v_pk_mul_f32 v[122:123], v[122:123], v[120:121]
	v_lshlrev_b32_e32 v120, 16, v159
	v_and_b32_e32 v121, 0xffff0000, v159
	v_pk_mul_f32 v[120:121], v[124:125], v[120:121]
	v_mul_f32_e32 v124, v123, v123
	v_mul_f32_e32 v158, v121, v121
	v_pk_fma_f32 v[124:125], v[122:123], v[122:123], v[124:125] op_sel_hi:[1,1,0]
	v_pk_fma_f32 v[158:159], v[120:121], v[120:121], v[158:159] op_sel_hi:[1,1,0]
	v_pk_add_f32 v[66:67], v[66:67], v[140:141] op_sel_hi:[1,0]
	v_pk_add_f32 v[124:125], v[124:125], v[158:159]
	v_pk_add_f32 v[68:69], v[68:69], v[140:141] op_sel_hi:[1,0]
	v_pk_add_f32 v[158:159], v[174:175], v[124:125]
	s_waitcnt vmcnt(12)
	v_lshlrev_b32_e32 v124, 16, v160
	v_and_b32_e32 v125, 0xffff0000, v160
	v_pk_mul_f32 v[124:125], v[126:127], v[124:125]
	v_lshlrev_b32_e32 v126, 16, v161
	v_and_b32_e32 v127, 0xffff0000, v161
	v_pk_mul_f32 v[126:127], v[128:129], v[126:127]
	v_mul_f32_e32 v128, v125, v125
	v_mul_f32_e32 v160, v127, v127
	v_pk_fma_f32 v[128:129], v[124:125], v[124:125], v[128:129] op_sel_hi:[1,1,0]
	v_pk_fma_f32 v[160:161], v[126:127], v[126:127], v[160:161] op_sel_hi:[1,1,0]
	v_pk_add_f32 v[70:71], v[70:71], v[140:141] op_sel_hi:[1,0]
	v_pk_add_f32 v[128:129], v[128:129], v[160:161]
	v_pk_add_f32 v[72:73], v[72:73], v[140:141] op_sel_hi:[1,0]
	v_pk_add_f32 v[128:129], v[158:159], v[128:129]
	v_pk_add_f32 v[74:75], v[74:75], v[140:141] op_sel_hi:[1,0]
	s_waitcnt vmcnt(11)
	v_lshlrev_b32_e32 v158, 16, v162
	v_and_b32_e32 v159, 0xffff0000, v162
	v_pk_mul_f32 v[98:99], v[98:99], v[158:159]
	v_lshlrev_b32_e32 v158, 16, v163
	v_and_b32_e32 v159, 0xffff0000, v163
	v_pk_mul_f32 v[100:101], v[100:101], v[158:159]
	v_mul_f32_e32 v158, v99, v99
	v_mul_f32_e32 v160, v101, v101
	v_pk_fma_f32 v[158:159], v[98:99], v[98:99], v[158:159] op_sel_hi:[1,1,0]
	v_pk_fma_f32 v[160:161], v[100:101], v[100:101], v[160:161] op_sel_hi:[1,1,0]
	v_pk_add_f32 v[76:77], v[76:77], v[140:141] op_sel_hi:[1,0]
	v_pk_add_f32 v[158:159], v[158:159], v[160:161]
	v_pk_add_f32 v[78:79], v[78:79], v[140:141] op_sel_hi:[1,0]
	v_pk_add_f32 v[158:159], v[128:129], v[158:159]
	s_waitcnt vmcnt(10)
	v_lshlrev_b32_e32 v128, 16, v164
	v_and_b32_e32 v129, 0xffff0000, v164
	v_pk_mul_f32 v[102:103], v[102:103], v[128:129]
	v_lshlrev_b32_e32 v128, 16, v165
	v_and_b32_e32 v129, 0xffff0000, v165
	v_pk_mul_f32 v[128:129], v[104:105], v[128:129]
	v_mul_f32_e32 v104, v103, v103
	v_mul_f32_e32 v160, v129, v129
	v_pk_fma_f32 v[104:105], v[102:103], v[102:103], v[104:105] op_sel_hi:[1,1,0]
	v_pk_fma_f32 v[160:161], v[128:129], v[128:129], v[160:161] op_sel_hi:[1,1,0]
	v_pk_add_f32 v[80:81], v[80:81], v[140:141] op_sel_hi:[1,0]
	v_pk_add_f32 v[104:105], v[104:105], v[160:161]
	s_nop 0
	v_pk_add_f32 v[158:159], v[158:159], v[104:105]
	s_waitcnt vmcnt(9)
; __device__ __forceinline__ void gmlp_unit(const GmlpP& P, int b, int ch, LAS unsigned char* lds, int wave, int lane_in) {
;     ...
;         for (int mt = 0; mt < 4; ++mt)
; #pragma unroll
;             for (int e4 = 0; e4 < 4; ++e4) {
;                 const u32x2 raw = uraw[mt][e4];
;                 const float u0 = __builtin_bit_cast(float, raw.x << 16), u1 = __builtin_bit_cast(float, raw.x & 0xffff0000u);
;                 const float u2 = __builtin_bit_cast(float, raw.y << 16), u3 = __builtin_bit_cast(float, raw.y & 0xffff0000u);
;                 float m0 = u0 * (acc[mt][nt][4 * e4] + bsv), m1 = u1 * (acc[mt][nt][4 * e4 + 1] + bsv), m2 = u2 * (acc[mt][nt][4 * e4 + 2] + bsv), m3 = u3 * (acc[mt][nt][4 * e4 + 3] + bsv);
;                 acc[mt][nt][4 * e4] = m0; acc[mt][nt][4 * e4 + 1] = m1; acc[mt][nt][4 * e4 + 2] = m2; acc[mt][nt][4 * e4 + 3] = m3;
;                 ss += (m0 * m0 + m1 * m1) + (m2 * m2 + m3 * m3);
;             }
	v_lshlrev_b32_e32 v104, 16, v166
	v_and_b32_e32 v105, 0xffff0000, v166
	v_pk_mul_f32 v[106:107], v[106:107], v[104:105]
	v_lshlrev_b32_e32 v104, 16, v167
	v_and_b32_e32 v105, 0xffff0000, v167
	v_pk_mul_f32 v[104:105], v[108:109], v[104:105]
	v_mul_f32_e32 v108, v107, v107
	v_mul_f32_e32 v160, v105, v105
	v_pk_fma_f32 v[108:109], v[106:107], v[106:107], v[108:109] op_sel_hi:[1,1,0]
	v_pk_fma_f32 v[160:161], v[104:105], v[104:105], v[160:161] op_sel_hi:[1,1,0]
	s_nop 0
	v_pk_add_f32 v[108:109], v[108:109], v[160:161]
	s_nop 0
	v_pk_add_f32 v[158:159], v[158:159], v[108:109]
	s_waitcnt vmcnt(8)
	v_lshlrev_b32_e32 v108, 16, v168
	v_and_b32_e32 v109, 0xffff0000, v168
	v_pk_mul_f32 v[108:109], v[110:111], v[108:109]
	v_lshlrev_b32_e32 v110, 16, v169
	v_and_b32_e32 v111, 0xffff0000, v169
	v_pk_mul_f32 v[110:111], v[112:113], v[110:111]
	v_mul_f32_e32 v112, v109, v109
	v_mul_f32_e32 v160, v111, v111
	v_pk_fma_f32 v[112:113], v[108:109], v[108:109], v[112:113] op_sel_hi:[1,1,0]
	v_pk_fma_f32 v[160:161], v[110:111], v[110:111], v[160:161] op_sel_hi:[1,1,0]
	s_nop 0
	v_pk_add_f32 v[112:113], v[112:113], v[160:161]
	s_nop 0
	v_pk_add_f32 v[112:113], v[158:159], v[112:113]
	s_waitcnt vmcnt(7)
	v_lshlrev_b32_e32 v158, 16, v170
	v_and_b32_e32 v159, 0xffff0000, v170
	v_pk_mul_f32 v[82:83], v[82:83], v[158:159]
	v_lshlrev_b32_e32 v158, 16, v171
	v_and_b32_e32 v159, 0xffff0000, v171
	v_pk_mul_f32 v[84:85], v[84:85], v[158:159]
	v_mul_f32_e32 v158, v83, v83
	v_mul_f32_e32 v160, v85, v85
	v_pk_fma_f32 v[158:159], v[82:83], v[82:83], v[158:159] op_sel_hi:[1,1,0]
	v_pk_fma_f32 v[160:161], v[84:85], v[84:85], v[160:161] op_sel_hi:[1,1,0]
	s_nop 0
	v_pk_add_f32 v[158:159], v[158:159], v[160:161]
	s_nop 0
	v_pk_add_f32 v[158:159], v[112:113], v[158:159]
	s_waitcnt vmcnt(6)
	v_lshlrev_b32_e32 v112, 16, v172
	v_and_b32_e32 v113, 0xffff0000, v172
	v_pk_mul_f32 v[86:87], v[86:87], v[112:113]
	v_lshlrev_b32_e32 v112, 16, v173
	v_and_b32_e32 v113, 0xffff0000, v173
	v_pk_mul_f32 v[112:113], v[88:89], v[112:113]
	v_mul_f32_e32 v88, v87, v87
	v_mul_f32_e32 v160, v113, v113
	v_pk_fma_f32 v[88:89], v[86:87], v[86:87], v[88:89] op_sel_hi:[1,1,0]
	v_pk_fma_f32 v[160:161], v[112:113], v[112:113], v[160:161] op_sel_hi:[1,1,0]
	s_nop 0
	v_pk_add_f32 v[88:89], v[88:89], v[160:161]
	s_nop 0
	v_pk_add_f32 v[158:159], v[158:159], v[88:89]
	s_waitcnt vmcnt(5)
	v_lshlrev_b32_e32 v88, 16, v180
	v_and_b32_e32 v89, 0xffff0000, v180
	v_pk_mul_f32 v[90:91], v[90:91], v[88:89]
	v_lshlrev_b32_e32 v88, 16, v181
	v_and_b32_e32 v89, 0xffff0000, v181
	v_pk_mul_f32 v[88:89], v[92:93], v[88:89]
	v_mul_f32_e32 v92, v91, v91
	v_mul_f32_e32 v160, v89, v89
	v_pk_fma_f32 v[92:93], v[90:91], v[90:91], v[92:93] op_sel_hi:[1,1,0]
	v_pk_fma_f32 v[160:161], v[88:89], v[88:89], v[160:161] op_sel_hi:[1,1,0]
	s_nop 0
	v_pk_add_f32 v[92:93], v[92:93], v[160:161]
	s_nop 0
	v_pk_add_f32 v[158:159], v[158:159], v[92:93]
	s_waitcnt vmcnt(4)
	v_lshlrev_b32_e32 v92, 16, v152
	v_and_b32_e32 v93, 0xffff0000, v152
	v_pk_mul_f32 v[92:93], v[94:95], v[92:93]
	v_lshlrev_b32_e32 v94, 16, v153
	v_and_b32_e32 v95, 0xffff0000, v153
	v_pk_mul_f32 v[94:95], v[96:97], v[94:95]
	v_mul_f32_e32 v96, v93, v93
	v_mul_f32_e32 v152, v95, v95
	v_pk_fma_f32 v[96:97], v[92:93], v[92:93], v[96:97] op_sel_hi:[1,1,0]
	v_pk_fma_f32 v[152:153], v[94:95], v[94:95], v[152:153] op_sel_hi:[1,1,0]
	s_nop 0
	v_pk_add_f32 v[96:97], v[96:97], v[152:153]
	s_waitcnt vmcnt(3)
	v_lshlrev_b32_e32 v152, 16, v150
	v_and_b32_e32 v153, 0xffff0000, v150
	v_lshlrev_b32_e32 v150, 16, v151
	v_and_b32_e32 v151, 0xffff0000, v151
	v_pk_mul_f32 v[66:67], v[66:67], v[152:153]
	v_pk_mul_f32 v[68:69], v[68:69], v[150:151]
	v_mul_f32_e32 v150, v67, v67
	v_mul_f32_e32 v152, v69, v69
	v_pk_fma_f32 v[150:151], v[66:67], v[66:67], v[150:151] op_sel_hi:[1,1,0]
	v_pk_fma_f32 v[152:153], v[68:69], v[68:69], v[152:153] op_sel_hi:[1,1,0]
	v_pk_add_f32 v[96:97], v[158:159], v[96:97]
	v_pk_add_f32 v[150:151], v[150:151], v[152:153]
	s_nop 0
	v_pk_add_f32 v[150:151], v[96:97], v[150:151]
	s_waitcnt vmcnt(2)
	v_lshlrev_b32_e32 v96, 16, v136
	v_and_b32_e32 v97, 0xffff0000, v136
	v_pk_mul_f32 v[70:71], v[70:71], v[96:97]
	v_lshlrev_b32_e32 v96, 16, v137
	v_and_b32_e32 v97, 0xffff0000, v137
	v_pk_mul_f32 v[96:97], v[72:73], v[96:97]
	v_mul_f32_e32 v72, v71, v71
	v_mul_f32_e32 v136, v97, v97
	v_pk_fma_f32 v[72:73], v[70:71], v[70:71], v[72:73] op_sel_hi:[1,1,0]
	v_pk_fma_f32 v[136:137], v[96:97], v[96:97], v[136:137] op_sel_hi:[1,1,0]
	s_nop 0
	v_pk_add_f32 v[72:73], v[72:73], v[136:137]
	s_nop 0
	v_pk_add_f32 v[136:137], v[150:151], v[72:73]
	s_waitcnt vmcnt(1)
	v_lshlrev_b32_e32 v72, 16, v134
	v_and_b32_e32 v73, 0xffff0000, v134
	v_pk_mul_f32 v[74:75], v[74:75], v[72:73]
	v_lshlrev_b32_e32 v72, 16, v135
	v_and_b32_e32 v73, 0xffff0000, v135
	v_pk_mul_f32 v[72:73], v[76:77], v[72:73]
	v_mul_f32_e32 v76, v75, v75
	v_mul_f32_e32 v134, v73, v73
	v_pk_fma_f32 v[76:77], v[74:75], v[74:75], v[76:77] op_sel_hi:[1,1,0]
	v_pk_fma_f32 v[134:135], v[72:73], v[72:73], v[134:135] op_sel_hi:[1,1,0]
	s_nop 0
	v_pk_add_f32 v[76:77], v[76:77], v[134:135]
	s_nop 0
	v_pk_add_f32 v[134:135], v[136:137], v[76:77]
	s_waitcnt vmcnt(0)
; __device__ __forceinline__ void gmlp_unit(const GmlpP& P, int b, int ch, LAS unsigned char* lds, int wave, int lane_in) {
;     ...
;     for (int nt = 0; nt < 2; ++nt) {
;         const int t = 32 * (nt == 0 ? tt0 : tt1) + r32;
;         const float bsv = P.bs[gI * 128 + t];
;         const bf16_t* up = P.U + (tok0 + t) * GW + gI * 128 + 4 * h;
;         float ss = 0.f;
;         u32x2 uraw[4][4];
; #pragma unroll
;         for (int mt = 0; mt < 4; ++mt)
; #pragma unroll
;             for (int e4 = 0; e4 < 4; ++e4) uraw[mt][e4] = *(const u32x2*)(up + 32 * mt + 8 * e4);
; #pragma unroll
;         for (int mt = 0; mt < 4; ++mt)
; #pragma unroll
;             for (int e4 = 0; e4 < 4; ++e4) {
;                 const u32x2 raw = uraw[mt][e4];
;                 const float u0 = __builtin_bit_cast(float, raw.x << 16), u1 = __builtin_bit_cast(float, raw.x & 0xffff0000u);
;                 const float u2 = __builtin_bit_cast(float, raw.y << 16), u3 = __builtin_bit_cast(float, raw.y & 0xffff0000u);
;                 float m0 = u0 * (acc[mt][nt][4 * e4] + bsv), m1 = u1 * (acc[mt][nt][4 * e4 + 1] + bsv), m2 = u2 * (acc[mt][nt][4 * e4 + 2] + bsv), m3 = u3 * (acc[mt][nt][4 * e4 + 3] + bsv);
;                 acc[mt][nt][4 * e4] = m0; acc[mt][nt][4 * e4 + 1] = m1; acc[mt][nt][4 * e4 + 2] = m2; acc[mt][nt][4 * e4 + 3] = m3;
;                 ss += (m0 * m0 + m1 * m1) + (m2 * m2 + m3 * m3);
;             }
;         ss = xor32_sum(ss);
;         if (h == 0) ssqg[gI * 128 + t] = ss;
;     }
	v_lshlrev_b32_e32 v76, 16, v132
	v_and_b32_e32 v77, 0xffff0000, v132
	v_pk_mul_f32 v[76:77], v[78:79], v[76:77]
	v_lshlrev_b32_e32 v78, 16, v133
	v_and_b32_e32 v79, 0xffff0000, v133
	v_pk_mul_f32 v[78:79], v[80:81], v[78:79]
	v_mul_f32_e32 v80, v77, v77
	v_mul_f32_e32 v132, v79, v79
	v_pk_fma_f32 v[80:81], v[76:77], v[76:77], v[80:81] op_sel_hi:[1,1,0]
	v_pk_fma_f32 v[132:133], v[78:79], v[78:79], v[132:133] op_sel_hi:[1,1,0]
	s_nop 0
	v_pk_add_f32 v[80:81], v[80:81], v[132:133]
	s_nop 0
	v_pk_add_f32 v[80:81], v[134:135], v[80:81]
	s_nop 0
	v_mov_b32_e32 v81, v80
	s_nop 1
	v_permlane32_swap_b32_e32 v80, v81
	s_and_saveexec_b64 s[26:27], vcc
	v_add_f32_e32 v80, v80, v81
	v_lshl_add_u32 v81, v148, 2, 0
	v_add_u32_e32 v81, 0x22000, v81
	ds_write_b32 v81, v80
	s_or_b64 exec, exec, s[26:27]
	v_add_u32_e32 v140, s31, v154
	v_lshl_add_u64 v[80:81], v[140:141], 0, s[6:7]
	v_lshl_add_u64 v[80:81], v[80:81], 2, s[40:41]
	global_load_dword v150, v[80:81], off offset:256
	v_or_b32_e32 v158, s23, v154
	v_or_b32_e32 v139, s50, v158
	v_lshlrev_b32_e32 v140, 10, v139
	v_lshl_add_u64 v[152:153], v[146:147], 0, v[140:141]
	v_bfe_u32 v234, v0, 5, 1
	v_lshlrev_b32_e32 v234, 3, v234
	v_mov_b32_e32 v235, 0
	v_lshl_add_u64 v[234:235], v[152:153], 0, v[234:235]
	v_and_b32_e32 v237, 63, v0
	v_lshrrev_b32_e32 v240, 1, v237
	v_and_b32_e32 v241, 1, v237
	v_and_b32_e32 v238, 31, v237
	v_lshrrev_b32_e32 v239, 5, v237
	v_lshl_add_u32 v236, v238, 1, v239
	v_lshlrev_b32_e32 v236, 2, v236
	v_sub_u32_e32 v238, v240, v238
	v_sub_u32_e32 v239, v241, v239
	v_lshlrev_b32_e32 v238, 10, v238
	v_lshl_add_u32 v238, v239, 4, v238
	v_ashrrev_i32_e32 v239, 31, v238
	v_lshl_add_u64 v[234:235], v[234:235], 0, v[238:239]
	global_load_dwordx4 v[202:205], v[234:235], off
	global_load_dwordx4 v[206:209], v[234:235], off offset:32
	global_load_dwordx4 v[210:213], v[234:235], off offset:64
	global_load_dwordx4 v[214:217], v[234:235], off offset:96
	global_load_dwordx4 v[218:221], v[234:235], off offset:128
	global_load_dwordx4 v[222:225], v[234:235], off offset:160
	global_load_dwordx4 v[226:229], v[234:235], off offset:192
	global_load_dwordx4 v[230:233], v[234:235], off offset:224
	s_waitcnt vmcnt(0)
	ds_bpermute_b32 v202, v236, v202
	ds_bpermute_b32 v203, v236, v203
	ds_bpermute_b32 v204, v236, v204
	ds_bpermute_b32 v205, v236, v205
	ds_bpermute_b32 v206, v236, v206
	ds_bpermute_b32 v207, v236, v207
	ds_bpermute_b32 v208, v236, v208
	ds_bpermute_b32 v209, v236, v209
	ds_bpermute_b32 v210, v236, v210
	ds_bpermute_b32 v211, v236, v211
	ds_bpermute_b32 v212, v236, v212
	ds_bpermute_b32 v213, v236, v213
	ds_bpermute_b32 v214, v236, v214
	ds_bpermute_b32 v215, v236, v215
	ds_bpermute_b32 v216, v236, v216
	ds_bpermute_b32 v217, v236, v217
	ds_bpermute_b32 v218, v236, v218
	ds_bpermute_b32 v219, v236, v219
	ds_bpermute_b32 v220, v236, v220
	ds_bpermute_b32 v221, v236, v221
	ds_bpermute_b32 v222, v236, v222
	ds_bpermute_b32 v223, v236, v223
	ds_bpermute_b32 v224, v236, v224
	ds_bpermute_b32 v225, v236, v225
	ds_bpermute_b32 v226, v236, v226
	ds_bpermute_b32 v227, v236, v227
	ds_bpermute_b32 v228, v236, v228
	ds_bpermute_b32 v229, v236, v229
	ds_bpermute_b32 v230, v236, v230
	ds_bpermute_b32 v231, v236, v231
	ds_bpermute_b32 v232, v236, v232
	ds_bpermute_b32 v233, v236, v233
	s_waitcnt lgkmcnt(0)
	v_permlane32_swap_b32_e32 v202, v204
	v_permlane32_swap_b32_e32 v203, v205
	v_permlane32_swap_b32_e32 v206, v208
	v_permlane32_swap_b32_e32 v207, v209
	v_permlane32_swap_b32_e32 v210, v212
	v_permlane32_swap_b32_e32 v211, v213
	v_permlane32_swap_b32_e32 v214, v216
	v_permlane32_swap_b32_e32 v215, v217
	v_permlane32_swap_b32_e32 v218, v220
	v_permlane32_swap_b32_e32 v219, v221
	v_permlane32_swap_b32_e32 v222, v224
	v_permlane32_swap_b32_e32 v223, v225
	v_permlane32_swap_b32_e32 v226, v228
	v_permlane32_swap_b32_e32 v227, v229
	v_permlane32_swap_b32_e32 v230, v232
	v_permlane32_swap_b32_e32 v231, v233
	v_mov_b32_e32 v160, v202
	v_mov_b32_e32 v161, v203
	v_mov_b32_e32 v162, v204
	v_mov_b32_e32 v163, v205
	v_mov_b32_e32 v164, v206
	v_mov_b32_e32 v165, v207
	v_mov_b32_e32 v166, v208
	v_mov_b32_e32 v167, v209
	v_mov_b32_e32 v168, v210
	v_mov_b32_e32 v169, v211
	v_mov_b32_e32 v170, v212
	v_mov_b32_e32 v171, v213
	v_mov_b32_e32 v172, v214
	v_mov_b32_e32 v173, v215
	v_mov_b32_e32 v174, v216
	v_mov_b32_e32 v175, v217
	v_mov_b32_e32 v154, v218
	v_mov_b32_e32 v155, v219
	v_mov_b32_e32 v146, v220
	v_mov_b32_e32 v147, v221
	v_mov_b32_e32 v134, v222
	v_mov_b32_e32 v135, v223
	v_mov_b32_e32 v80, v224
	v_mov_b32_e32 v81, v225
	v_mov_b32_e32 v132, v226
	v_mov_b32_e32 v133, v227
	v_mov_b32_e32 v136, v228
	v_mov_b32_e32 v137, v229
	v_mov_b32_e32 v148, v230
	v_mov_b32_e32 v149, v231
	v_mov_b32_e32 v152, v232
	v_mov_b32_e32 v153, v233
	s_waitcnt vmcnt(12)
	v_lshlrev_b32_e32 v186, 16, v166
	s_waitcnt vmcnt(11)
; __device__ __forceinline__ void gmlp_unit(const GmlpP& P, int b, int ch, LAS unsigned char* lds, int wave, int lane_in) {
;     ...
;         for (int mt = 0; mt < 4; ++mt)
; #pragma unroll
;             for (int e4 = 0; e4 < 4; ++e4) {
;                 const u32x2 raw = uraw[mt][e4];
;                 const float u0 = __builtin_bit_cast(float, raw.x << 16), u1 = __builtin_bit_cast(float, raw.x & 0xffff0000u);
;                 const float u2 = __builtin_bit_cast(float, raw.y << 16), u3 = __builtin_bit_cast(float, raw.y & 0xffff0000u);
;                 float m0 = u0 * (acc[mt][nt][4 * e4] + bsv), m1 = u1 * (acc[mt][nt][4 * e4 + 1] + bsv), m2 = u2 * (acc[mt][nt][4 * e4 + 2] + bsv), m3 = u3 * (acc[mt][nt][4 * e4 + 3] + bsv);
;                 acc[mt][nt][4 * e4] = m0; acc[mt][nt][4 * e4 + 1] = m1; acc[mt][nt][4 * e4 + 2] = m2; acc[mt][nt][4 * e4 + 3] = m3;
;                 ss += (m0 * m0 + m1 * m1) + (m2 * m2 + m3 * m3);
;             }
	v_lshlrev_b32_e32 v188, 16, v168
	v_and_b32_e32 v189, 0xffff0000, v168
	v_lshlrev_b32_e32 v168, 16, v169
	v_and_b32_e32 v169, 0xffff0000, v169
	v_and_b32_e32 v187, 0xffff0000, v166
	v_lshlrev_b32_e32 v166, 16, v167
	v_pk_add_f32 v[50:51], v[50:51], v[150:151] op_sel_hi:[1,0]
	v_pk_add_f32 v[52:53], v[52:53], v[150:151] op_sel_hi:[1,0]
	v_pk_add_f32 v[54:55], v[54:55], v[150:151] op_sel_hi:[1,0]
	v_pk_add_f32 v[56:57], v[56:57], v[150:151] op_sel_hi:[1,0]
	v_pk_add_f32 v[176:177], v[58:59], v[150:151] op_sel_hi:[1,0]
	v_pk_add_f32 v[178:179], v[60:61], v[150:151] op_sel_hi:[1,0]
	v_pk_add_f32 v[184:185], v[36:37], v[150:151] op_sel_hi:[1,0]
	v_lshlrev_b32_e32 v36, 16, v160
	v_and_b32_e32 v37, 0xffff0000, v160
	v_lshlrev_b32_e32 v58, 16, v161
	v_and_b32_e32 v59, 0xffff0000, v161
	v_lshlrev_b32_e32 v60, 16, v162
	v_and_b32_e32 v61, 0xffff0000, v162
	v_lshlrev_b32_e32 v160, 16, v163
	v_and_b32_e32 v161, 0xffff0000, v163
	v_pk_add_f32 v[180:181], v[62:63], v[150:151] op_sel_hi:[1,0]
	v_pk_add_f32 v[182:183], v[64:65], v[150:151] op_sel_hi:[1,0]
	v_lshlrev_b32_e32 v162, 16, v164
	v_and_b32_e32 v163, 0xffff0000, v164
	v_lshlrev_b32_e32 v164, 16, v165
	v_and_b32_e32 v165, 0xffff0000, v165
	v_pk_mul_f32 v[64:65], v[50:51], v[36:37]
	v_pk_mul_f32 v[62:63], v[52:53], v[58:59]
	v_pk_mul_f32 v[60:61], v[54:55], v[60:61]
	v_pk_mul_f32 v[58:59], v[56:57], v[160:161]
	v_pk_add_f32 v[34:35], v[34:35], v[150:151] op_sel_hi:[1,0]
	v_pk_mul_f32 v[56:57], v[176:177], v[162:163]
	v_pk_mul_f32 v[54:55], v[178:179], v[164:165]
	v_mul_f32_e32 v140, v65, v65
	v_mul_f32_e32 v160, v63, v63
	v_mul_f32_e32 v162, v61, v61
	v_mul_f32_e32 v164, v59, v59
	v_pk_mul_f32 v[36:37], v[34:35], v[188:189]
	v_pk_mul_f32 v[34:35], v[184:185], v[168:169]
	v_pk_fma_f32 v[184:185], v[64:65], v[64:65], v[140:141] op_sel_hi:[1,1,0]
	v_pk_fma_f32 v[160:161], v[62:63], v[62:63], v[160:161] op_sel_hi:[1,1,0]
	v_pk_fma_f32 v[162:163], v[60:61], v[60:61], v[162:163] op_sel_hi:[1,1,0]
	v_pk_fma_f32 v[164:165], v[58:59], v[58:59], v[164:165] op_sel_hi:[1,1,0]
	v_and_b32_e32 v167, 0xffff0000, v167
	v_pk_add_f32 v[160:161], v[184:185], v[160:161]
	v_pk_add_f32 v[162:163], v[162:163], v[164:165]
	v_pk_mul_f32 v[52:53], v[180:181], v[186:187]
	v_pk_mul_f32 v[50:51], v[182:183], v[166:167]
	v_mul_f32_e32 v166, v57, v57
	v_mul_f32_e32 v168, v55, v55
	v_pk_add_f32 v[160:161], v[160:161], v[162:163]
	s_waitcnt vmcnt(10)
	v_lshlrev_b32_e32 v162, 16, v170
	v_and_b32_e32 v163, 0xffff0000, v170
	v_pk_add_f32 v[38:39], v[38:39], v[150:151] op_sel_hi:[1,0]
	v_mul_f32_e32 v176, v53, v53
	v_mul_f32_e32 v178, v51, v51
	v_pk_fma_f32 v[166:167], v[56:57], v[56:57], v[166:167] op_sel_hi:[1,1,0]
	v_pk_fma_f32 v[168:169], v[54:55], v[54:55], v[168:169] op_sel_hi:[1,1,0]
	v_pk_mul_f32 v[38:39], v[38:39], v[162:163]
	v_lshlrev_b32_e32 v162, 16, v171
	v_and_b32_e32 v163, 0xffff0000, v171
	v_pk_add_f32 v[40:41], v[40:41], v[150:151] op_sel_hi:[1,0]
	v_mul_f32_e32 v180, v37, v37
	v_mul_f32_e32 v182, v35, v35
	v_pk_fma_f32 v[176:177], v[52:53], v[52:53], v[176:177] op_sel_hi:[1,1,0]
	v_pk_fma_f32 v[178:179], v[50:51], v[50:51], v[178:179] op_sel_hi:[1,1,0]
	v_pk_add_f32 v[164:165], v[166:167], v[168:169]
	v_pk_mul_f32 v[40:41], v[40:41], v[162:163]
	v_mul_f32_e32 v140, v39, v39
	v_pk_fma_f32 v[180:181], v[36:37], v[36:37], v[180:181] op_sel_hi:[1,1,0]
	v_pk_fma_f32 v[182:183], v[34:35], v[34:35], v[182:183] op_sel_hi:[1,1,0]
	v_pk_add_f32 v[166:167], v[176:177], v[178:179]
	v_pk_add_f32 v[160:161], v[160:161], v[164:165]
	v_pk_fma_f32 v[162:163], v[38:39], v[38:39], v[140:141] op_sel_hi:[1,1,0]
	v_mul_f32_e32 v140, v41, v41
	v_pk_add_f32 v[168:169], v[180:181], v[182:183]
	v_pk_add_f32 v[160:161], v[160:161], v[166:167]
	v_pk_fma_f32 v[164:165], v[40:41], v[40:41], v[140:141] op_sel_hi:[1,1,0]
	v_pk_add_f32 v[160:161], v[160:161], v[168:169]
	v_pk_add_f32 v[162:163], v[162:163], v[164:165]
	v_pk_add_f32 v[42:43], v[42:43], v[150:151] op_sel_hi:[1,0]
	v_pk_add_f32 v[160:161], v[160:161], v[162:163]
	s_waitcnt vmcnt(9)
	v_lshlrev_b32_e32 v162, 16, v172
	v_and_b32_e32 v163, 0xffff0000, v172
	v_pk_mul_f32 v[42:43], v[42:43], v[162:163]
	v_lshlrev_b32_e32 v162, 16, v173
	v_and_b32_e32 v163, 0xffff0000, v173
	v_pk_add_f32 v[44:45], v[44:45], v[150:151] op_sel_hi:[1,0]
	v_mul_f32_e32 v140, v43, v43
	v_pk_mul_f32 v[44:45], v[44:45], v[162:163]
	v_pk_fma_f32 v[162:163], v[42:43], v[42:43], v[140:141] op_sel_hi:[1,1,0]
	v_mul_f32_e32 v140, v45, v45
	v_pk_fma_f32 v[164:165], v[44:45], v[44:45], v[140:141] op_sel_hi:[1,1,0]
	v_pk_add_f32 v[46:47], v[46:47], v[150:151] op_sel_hi:[1,0]
	v_pk_add_f32 v[162:163], v[162:163], v[164:165]
	v_pk_add_f32 v[48:49], v[48:49], v[150:151] op_sel_hi:[1,0]
	v_pk_add_f32 v[160:161], v[160:161], v[162:163]
	s_waitcnt vmcnt(8)
	v_lshlrev_b32_e32 v162, 16, v174
	v_and_b32_e32 v163, 0xffff0000, v174
	v_pk_mul_f32 v[46:47], v[46:47], v[162:163]
	v_lshlrev_b32_e32 v162, 16, v175
	v_and_b32_e32 v163, 0xffff0000, v175
	v_pk_mul_f32 v[48:49], v[48:49], v[162:163]
	v_mul_f32_e32 v140, v47, v47
	v_pk_fma_f32 v[162:163], v[46:47], v[46:47], v[140:141] op_sel_hi:[1,1,0]
	v_mul_f32_e32 v140, v49, v49
	v_pk_fma_f32 v[164:165], v[48:49], v[48:49], v[140:141] op_sel_hi:[1,1,0]
	v_pk_add_f32 v[18:19], v[18:19], v[150:151] op_sel_hi:[1,0]
	v_pk_add_f32 v[162:163], v[162:163], v[164:165]
	v_pk_add_f32 v[20:21], v[20:21], v[150:151] op_sel_hi:[1,0]
	v_pk_add_f32 v[160:161], v[160:161], v[162:163]
	s_waitcnt vmcnt(7)
; __device__ __forceinline__ void gmlp_unit(const GmlpP& P, int b, int ch, LAS unsigned char* lds, int wave, int lane_in) {
;     ...
;         for (int mt = 0; mt < 4; ++mt)
; #pragma unroll
;             for (int e4 = 0; e4 < 4; ++e4) {
;                 const u32x2 raw = uraw[mt][e4];
;                 const float u0 = __builtin_bit_cast(float, raw.x << 16), u1 = __builtin_bit_cast(float, raw.x & 0xffff0000u);
;                 const float u2 = __builtin_bit_cast(float, raw.y << 16), u3 = __builtin_bit_cast(float, raw.y & 0xffff0000u);
;                 float m0 = u0 * (acc[mt][nt][4 * e4] + bsv), m1 = u1 * (acc[mt][nt][4 * e4 + 1] + bsv), m2 = u2 * (acc[mt][nt][4 * e4 + 2] + bsv), m3 = u3 * (acc[mt][nt][4 * e4 + 3] + bsv);
;                 acc[mt][nt][4 * e4] = m0; acc[mt][nt][4 * e4 + 1] = m1; acc[mt][nt][4 * e4 + 2] = m2; acc[mt][nt][4 * e4 + 3] = m3;
;                 ss += (m0 * m0 + m1 * m1) + (m2 * m2 + m3 * m3);
;             }
;         ss = xor32_sum(ss);
;         if (h == 0) ssqg[gI * 128 + t] = ss;
;     }
	v_lshlrev_b32_e32 v162, 16, v154
	v_and_b32_e32 v163, 0xffff0000, v154
	v_pk_mul_f32 v[18:19], v[18:19], v[162:163]
	v_lshlrev_b32_e32 v154, 16, v155
	v_and_b32_e32 v155, 0xffff0000, v155
	v_pk_mul_f32 v[20:21], v[20:21], v[154:155]
	v_mul_f32_e32 v140, v19, v19
	v_pk_fma_f32 v[154:155], v[18:19], v[18:19], v[140:141] op_sel_hi:[1,1,0]
	v_mul_f32_e32 v140, v21, v21
	v_pk_fma_f32 v[162:163], v[20:21], v[20:21], v[140:141] op_sel_hi:[1,1,0]
	v_pk_add_f32 v[22:23], v[22:23], v[150:151] op_sel_hi:[1,0]
	v_pk_add_f32 v[154:155], v[154:155], v[162:163]
	v_pk_add_f32 v[24:25], v[24:25], v[150:151] op_sel_hi:[1,0]
	v_pk_add_f32 v[154:155], v[160:161], v[154:155]
	s_waitcnt vmcnt(6)
	v_lshlrev_b32_e32 v160, 16, v146
	v_and_b32_e32 v161, 0xffff0000, v146
	v_pk_mul_f32 v[22:23], v[22:23], v[160:161]
	v_lshlrev_b32_e32 v146, 16, v147
	v_and_b32_e32 v147, 0xffff0000, v147
	v_pk_mul_f32 v[24:25], v[24:25], v[146:147]
	v_mul_f32_e32 v140, v23, v23
	v_pk_fma_f32 v[146:147], v[22:23], v[22:23], v[140:141] op_sel_hi:[1,1,0]
	v_mul_f32_e32 v140, v25, v25
	v_pk_fma_f32 v[160:161], v[24:25], v[24:25], v[140:141] op_sel_hi:[1,1,0]
	v_pk_add_f32 v[26:27], v[26:27], v[150:151] op_sel_hi:[1,0]
	v_pk_add_f32 v[146:147], v[146:147], v[160:161]
	v_pk_add_f32 v[28:29], v[28:29], v[150:151] op_sel_hi:[1,0]
	v_pk_add_f32 v[146:147], v[154:155], v[146:147]
	s_waitcnt vmcnt(5)
	v_lshlrev_b32_e32 v154, 16, v134
	v_and_b32_e32 v155, 0xffff0000, v134
	v_lshlrev_b32_e32 v134, 16, v135
	v_and_b32_e32 v135, 0xffff0000, v135
	v_pk_mul_f32 v[26:27], v[26:27], v[154:155]
	v_pk_mul_f32 v[28:29], v[28:29], v[134:135]
	v_mul_f32_e32 v134, v27, v27
	v_mul_f32_e32 v140, v29, v29
	v_pk_fma_f32 v[134:135], v[26:27], v[26:27], v[134:135] op_sel_hi:[1,1,0]
	v_pk_fma_f32 v[154:155], v[28:29], v[28:29], v[140:141] op_sel_hi:[1,1,0]
	v_pk_add_f32 v[30:31], v[30:31], v[150:151] op_sel_hi:[1,0]
	v_pk_add_f32 v[134:135], v[134:135], v[154:155]
	v_pk_add_f32 v[32:33], v[32:33], v[150:151] op_sel_hi:[1,0]
	v_pk_add_f32 v[134:135], v[146:147], v[134:135]
	s_waitcnt vmcnt(4)
	v_lshlrev_b32_e32 v146, 16, v80
	v_and_b32_e32 v147, 0xffff0000, v80
	v_lshlrev_b32_e32 v80, 16, v81
	v_and_b32_e32 v81, 0xffff0000, v81
	v_pk_mul_f32 v[30:31], v[30:31], v[146:147]
	v_pk_mul_f32 v[32:33], v[32:33], v[80:81]
	v_mul_f32_e32 v80, v31, v31
	v_mul_f32_e32 v140, v33, v33
	v_pk_fma_f32 v[80:81], v[30:31], v[30:31], v[80:81] op_sel_hi:[1,1,0]
	v_pk_fma_f32 v[146:147], v[32:33], v[32:33], v[140:141] op_sel_hi:[1,1,0]
	v_pk_add_f32 v[2:3], v[2:3], v[150:151] op_sel_hi:[1,0]
	v_pk_add_f32 v[80:81], v[80:81], v[146:147]
	v_pk_add_f32 v[4:5], v[4:5], v[150:151] op_sel_hi:[1,0]
	v_pk_add_f32 v[134:135], v[134:135], v[80:81]
	s_waitcnt vmcnt(3)
	v_lshlrev_b32_e32 v80, 16, v132
	v_and_b32_e32 v81, 0xffff0000, v132
	v_pk_mul_f32 v[80:81], v[2:3], v[80:81]
	v_lshlrev_b32_e32 v2, 16, v133
	v_and_b32_e32 v3, 0xffff0000, v133
	v_pk_mul_f32 v[132:133], v[4:5], v[2:3]
	v_mul_f32_e32 v2, v81, v81
	v_mul_f32_e32 v4, v133, v133
	v_pk_fma_f32 v[2:3], v[80:81], v[80:81], v[2:3] op_sel_hi:[1,1,0]
	v_pk_fma_f32 v[4:5], v[132:133], v[132:133], v[4:5] op_sel_hi:[1,1,0]
	v_pk_add_f32 v[6:7], v[6:7], v[150:151] op_sel_hi:[1,0]
	v_pk_add_f32 v[2:3], v[2:3], v[4:5]
	s_waitcnt vmcnt(2)
	v_lshlrev_b32_e32 v4, 16, v136
	v_and_b32_e32 v5, 0xffff0000, v136
	v_pk_add_f32 v[2:3], v[134:135], v[2:3]
	v_pk_mul_f32 v[134:135], v[6:7], v[4:5]
	v_lshlrev_b32_e32 v4, 16, v137
	v_and_b32_e32 v5, 0xffff0000, v137
	v_pk_add_f32 v[6:7], v[8:9], v[150:151] op_sel_hi:[1,0]
	s_nop 0
	v_pk_mul_f32 v[136:137], v[6:7], v[4:5]
	v_mul_f32_e32 v4, v135, v135
	v_mul_f32_e32 v6, v137, v137
	v_pk_fma_f32 v[4:5], v[134:135], v[134:135], v[4:5] op_sel_hi:[1,1,0]
	v_pk_fma_f32 v[6:7], v[136:137], v[136:137], v[6:7] op_sel_hi:[1,1,0]
	s_nop 0
	v_pk_add_f32 v[4:5], v[4:5], v[6:7]
	v_pk_add_f32 v[6:7], v[10:11], v[150:151] op_sel_hi:[1,0]
	v_pk_add_f32 v[2:3], v[2:3], v[4:5]
	s_waitcnt vmcnt(1)
	v_lshlrev_b32_e32 v4, 16, v148
	v_and_b32_e32 v5, 0xffff0000, v148
	v_pk_mul_f32 v[146:147], v[6:7], v[4:5]
	v_lshlrev_b32_e32 v4, 16, v149
	v_and_b32_e32 v5, 0xffff0000, v149
	v_pk_add_f32 v[6:7], v[12:13], v[150:151] op_sel_hi:[1,0]
	s_nop 0
	v_pk_mul_f32 v[148:149], v[6:7], v[4:5]
	v_mul_f32_e32 v4, v147, v147
	v_mul_f32_e32 v6, v149, v149
	v_pk_fma_f32 v[4:5], v[146:147], v[146:147], v[4:5] op_sel_hi:[1,1,0]
	v_pk_fma_f32 v[6:7], v[148:149], v[148:149], v[6:7] op_sel_hi:[1,1,0]
	s_nop 0
	v_pk_add_f32 v[4:5], v[4:5], v[6:7]
	v_pk_add_f32 v[6:7], v[14:15], v[150:151] op_sel_hi:[1,0]
	v_pk_add_f32 v[2:3], v[2:3], v[4:5]
	s_waitcnt vmcnt(0)
	v_lshlrev_b32_e32 v4, 16, v152
	v_and_b32_e32 v5, 0xffff0000, v152
	v_pk_mul_f32 v[14:15], v[6:7], v[4:5]
	v_lshlrev_b32_e32 v4, 16, v153
	v_and_b32_e32 v5, 0xffff0000, v153
	v_pk_add_f32 v[6:7], v[16:17], v[150:151] op_sel_hi:[1,0]
	s_nop 0
	v_pk_mul_f32 v[16:17], v[6:7], v[4:5]
	v_mul_f32_e32 v4, v15, v15
	v_mul_f32_e32 v6, v17, v17
	v_pk_fma_f32 v[4:5], v[14:15], v[14:15], v[4:5] op_sel_hi:[1,1,0]
	v_pk_fma_f32 v[6:7], v[16:17], v[16:17], v[6:7] op_sel_hi:[1,1,0]
	s_nop 0
	v_pk_add_f32 v[4:5], v[4:5], v[6:7]
	s_nop 0
	v_pk_add_f32 v[2:3], v[2:3], v[4:5]
	s_nop 0
	v_mov_b32_e32 v3, v2
	s_nop 1
	v_permlane32_swap_b32_e32 v2, v3
	s_and_saveexec_b64 s[26:27], vcc
	s_cbranch_execz .LBB0_536
	v_or_b32_e32 v4, s6, v158
	v_add_f32_e32 v2, v2, v3
	v_lshl_add_u32 v3, v4, 2, 0
	v_add_u32_e32 v3, 0x22000, v3
	ds_write_b32 v3, v2
	s_branch .LBB0_536
